# v63 + dec memattn2 q-wait moved behind the K/V load burst (both groups) + P4 dec_out all 32 operand loads in flight
# speedup vs baseline: 1.0202x; 1.0009x over previous
.LBB0_554:
	v_mov_b32_e32 v1, v0
	s_nop 0
	v_readfirstlane_b32 s2, v1
	s_ashr_i32 s47, s2, 6
	s_lshl_b32 s22, s47, 5
	s_ashr_i32 s23, s22, 31
	v_and_b32_e32 v132, 63, v1
	s_lshl_b64 s[2:3], s[22:23], 11
	s_waitcnt vmcnt(0)
	v_lshl_or_b32 v106, v132, 4, s2
	s_add_u32 s2, s20, s6
	v_lshlrev_b32_e32 v2, 3, v132
	v_mov_b32_e32 v107, s3
	s_addc_u32 s3, s21, s7
	global_load_dwordx2 v[108:109], v2, s[10:11]
	v_lshl_add_u64 v[2:3], s[2:3], 0, v[106:107]
	v_add_co_u32_e32 v4, vcc, s28, v2
	global_load_dwordx4 v[138:141], v[2:3], off nt
	global_load_dwordx4 v[98:101], v[2:3], off offset:2048 nt
	v_addc_co_u32_e32 v5, vcc, 0, v3, vcc
	v_add_co_u32_e32 v102, vcc, s29, v2
	v_addc_co_u32_e32 v103, vcc, 0, v3, vcc
	v_add_co_u32_e32 v6, vcc, s30, v2
	global_load_dwordx4 v[90:93], v[102:103], off nt
	global_load_dwordx4 v[86:89], v[102:103], off offset:2048 nt
	v_addc_co_u32_e32 v7, vcc, 0, v3, vcc
	v_add_co_u32_e32 v8, vcc, s31, v2
	s_nop 0
	v_addc_co_u32_e32 v9, vcc, 0, v3, vcc
	global_load_dwordx4 v[94:97], v[4:5], off offset:2048 nt
	global_load_dwordx4 v[78:81], v[6:7], off offset:2048 nt
	global_load_dwordx4 v[82:85], v[8:9], off offset:-4096 nt
	global_load_dwordx4 v[74:77], v[8:9], off nt
	v_add_co_u32_e32 v4, vcc, s33, v2
	s_nop 0
	v_addc_co_u32_e32 v5, vcc, 0, v3, vcc
	v_add_co_u32_e32 v6, vcc, s36, v2
	s_nop 0
	v_addc_co_u32_e32 v7, vcc, 0, v3, vcc
	global_load_dwordx4 v[66:69], v[8:9], off offset:2048 nt
	global_load_dwordx4 v[62:65], v[6:7], off offset:-4096 nt
	global_load_dwordx4 v[54:57], v[6:7], off nt
	global_load_dwordx4 v[50:53], v[6:7], off offset:2048 nt
	v_add_co_u32_e32 v6, vcc, s37, v2
	s_nop 1
	v_addc_co_u32_e32 v7, vcc, 0, v3, vcc
	v_add_co_u32_e32 v8, vcc, s38, v2
	s_nop 1
	v_addc_co_u32_e32 v9, vcc, 0, v3, vcc
	global_load_dwordx4 v[58:61], v[4:5], off offset:2048 nt
	global_load_dwordx4 v[42:45], v[6:7], off offset:2048 nt
	global_load_dwordx4 v[46:49], v[8:9], off offset:-4096 nt
	global_load_dwordx4 v[126:129], v[8:9], off nt
	v_add_co_u32_e32 v4, vcc, s39, v2
	s_nop 1
	v_addc_co_u32_e32 v5, vcc, 0, v3, vcc
	v_add_co_u32_e32 v6, vcc, s40, v2
	s_nop 1
	v_addc_co_u32_e32 v7, vcc, 0, v3, vcc
	global_load_dwordx4 v[122:125], v[8:9], off offset:2048 nt
	global_load_dwordx4 v[118:121], v[6:7], off offset:-4096 nt
	global_load_dwordx4 v[110:113], v[6:7], off nt
	global_load_dwordx4 v[70:73], v[6:7], off offset:2048 nt
	v_add_co_u32_e32 v6, vcc, s41, v2
	s_nop 1
	v_addc_co_u32_e32 v7, vcc, 0, v3, vcc
	v_add_co_u32_e32 v8, vcc, s42, v2
	s_nop 1
	v_addc_co_u32_e32 v9, vcc, 0, v3, vcc
	global_load_dwordx4 v[114:117], v[4:5], off offset:2048 nt
	global_load_dwordx4 v[34:37], v[6:7], off offset:2048 nt
	global_load_dwordx4 v[38:41], v[8:9], off offset:-4096 nt
	global_load_dwordx4 v[30:33], v[8:9], off nt
	v_add_co_u32_e32 v4, vcc, s43, v2
	s_nop 1
	v_addc_co_u32_e32 v5, vcc, 0, v3, vcc
	v_add_co_u32_e32 v6, vcc, s44, v2
	s_nop 1
	v_addc_co_u32_e32 v7, vcc, 0, v3, vcc
	v_add_co_u32_e32 v2, vcc, s45, v2
	global_load_dwordx4 v[26:29], v[8:9], off offset:2048 nt
	global_load_dwordx4 v[22:25], v[6:7], off offset:-4096 nt
	global_load_dwordx4 v[14:17], v[6:7], off nt
	global_load_dwordx4 v[10:13], v[6:7], off offset:2048 nt
	v_addc_co_u32_e32 v3, vcc, 0, v3, vcc
	global_load_dwordx4 v[18:21], v[4:5], off offset:2048 nt
	global_load_dwordx4 v[6:9], v[2:3], off nt
	s_nop 0
	global_load_dwordx4 v[102:105], v[102:103], off offset:-4096 nt
	s_nop 0
	global_load_dwordx4 v[2:5], v[2:3], off offset:2048 nt
	s_waitcnt vmcnt(32)
	v_lshlrev_b32_e32 v135, 16, v108
	v_and_b32_e32 v137, 0xffff0000, v108
	v_lshlrev_b32_e32 v136, 16, v109
	v_and_b32_e32 v134, 0xffff0000, v109
	v_and_b32_e32 v108, 31, v1
	v_cmp_eq_u32_e64 s[2:3], 0, v108
	v_lshlrev_b32_e32 v108, 5, v1
	v_and_b32_e32 v133, 0x400, v108
	s_waitcnt vmcnt(31)
	v_mul_f32_e32 v108, v139, v137
	v_fmac_f32_e32 v108, v138, v135
	v_fmac_f32_e32 v108, v140, v136
	v_fmac_f32_e32 v108, v141, v134
	s_lshl_b32 s23, s47, 7
	s_add_i32 s23, s23, 0
	v_add_f32_dpp v108, v108, v108 quad_perm:[1,0,3,2] row_mask:0xf bank_mask:0xf bound_ctrl:1
	v_add_u32_e32 v138, s23, v133
	s_nop 0
	v_add_f32_dpp v108, v108, v108 quad_perm:[2,3,0,1] row_mask:0xf bank_mask:0xf bound_ctrl:1
	s_nop 1
	v_add_f32_dpp v108, v108, v108 row_ror:4 row_mask:0xf bank_mask:0xf bound_ctrl:1
	s_nop 1
	v_add_f32_dpp v108, v108, v108 row_ror:8 row_mask:0xf bank_mask:0xf bound_ctrl:1
	v_mov_b32_e32 v109, v108
	s_nop 1
	v_permlane16_swap_b32_e32 v108, v109
	s_and_saveexec_b64 s[24:25], s[2:3]
	v_add_f32_e32 v108, v108, v109
	ds_write_b32 v138, v108
	s_or_b64 exec, exec, s[24:25]
	s_waitcnt vmcnt(30)
	v_mul_f32_e32 v99, v99, v137
	v_fmac_f32_e32 v99, v98, v135
	v_fmac_f32_e32 v99, v100, v136
	v_fmac_f32_e32 v99, v101, v134
	s_nop 1
	v_add_f32_dpp v98, v99, v99 quad_perm:[1,0,3,2] row_mask:0xf bank_mask:0xf bound_ctrl:1
	s_nop 1
	v_add_f32_dpp v98, v98, v98 quad_perm:[2,3,0,1] row_mask:0xf bank_mask:0xf bound_ctrl:1
	s_nop 1
	v_add_f32_dpp v98, v98, v98 row_ror:4 row_mask:0xf bank_mask:0xf bound_ctrl:1
	s_nop 1
	v_add_f32_dpp v98, v98, v98 row_ror:8 row_mask:0xf bank_mask:0xf bound_ctrl:1
	v_mov_b32_e32 v99, v98
	s_nop 1
	v_permlane16_swap_b32_e32 v98, v99
	s_and_saveexec_b64 s[24:25], s[2:3]
	v_add_f32_e32 v98, v98, v99
	ds_write_b32 v138, v98 offset:4
	s_or_b64 exec, exec, s[24:25]
	s_waitcnt vmcnt(1)
	v_mul_f32_e32 v98, v103, v137
	v_fmac_f32_e32 v98, v102, v135
	v_fmac_f32_e32 v98, v104, v136
	v_fmac_f32_e32 v98, v105, v134
	s_nop 1
	v_add_f32_dpp v98, v98, v98 quad_perm:[1,0,3,2] row_mask:0xf bank_mask:0xf bound_ctrl:1
	s_nop 1
	v_add_f32_dpp v98, v98, v98 quad_perm:[2,3,0,1] row_mask:0xf bank_mask:0xf bound_ctrl:1
	s_nop 1
	v_add_f32_dpp v98, v98, v98 row_ror:4 row_mask:0xf bank_mask:0xf bound_ctrl:1
	s_nop 1
	v_add_f32_dpp v98, v98, v98 row_ror:8 row_mask:0xf bank_mask:0xf bound_ctrl:1
	v_mov_b32_e32 v99, v98
	s_nop 1
	v_permlane16_swap_b32_e32 v98, v99
	s_and_saveexec_b64 s[24:25], s[2:3]
	v_add_f32_e32 v98, v98, v99
	ds_write_b32 v138, v98 offset:8
	s_or_b64 exec, exec, s[24:25]
	v_mul_f32_e32 v95, v95, v137
	v_fmac_f32_e32 v95, v94, v135
	v_fmac_f32_e32 v95, v96, v136
	v_fmac_f32_e32 v95, v97, v134
	s_nop 1
	v_add_f32_dpp v94, v95, v95 quad_perm:[1,0,3,2] row_mask:0xf bank_mask:0xf bound_ctrl:1
	s_nop 1
	v_add_f32_dpp v94, v94, v94 quad_perm:[2,3,0,1] row_mask:0xf bank_mask:0xf bound_ctrl:1
	s_nop 1
	v_add_f32_dpp v94, v94, v94 row_ror:4 row_mask:0xf bank_mask:0xf bound_ctrl:1
	s_nop 1
	v_add_f32_dpp v94, v94, v94 row_ror:8 row_mask:0xf bank_mask:0xf bound_ctrl:1
	v_mov_b32_e32 v95, v94
	s_nop 1
	v_permlane16_swap_b32_e32 v94, v95
	s_and_saveexec_b64 s[24:25], s[2:3]
	v_add_f32_e32 v94, v94, v95
	ds_write_b32 v138, v94 offset:12
	s_or_b64 exec, exec, s[24:25]
	v_mul_f32_e32 v91, v91, v137
	v_fmac_f32_e32 v91, v90, v135
	v_fmac_f32_e32 v91, v92, v136
	v_fmac_f32_e32 v91, v93, v134
	s_nop 1
	v_add_f32_dpp v90, v91, v91 quad_perm:[1,0,3,2] row_mask:0xf bank_mask:0xf bound_ctrl:1
	s_nop 1
	v_add_f32_dpp v90, v90, v90 quad_perm:[2,3,0,1] row_mask:0xf bank_mask:0xf bound_ctrl:1
	s_nop 1
	v_add_f32_dpp v90, v90, v90 row_ror:4 row_mask:0xf bank_mask:0xf bound_ctrl:1
	s_nop 1
	v_add_f32_dpp v90, v90, v90 row_ror:8 row_mask:0xf bank_mask:0xf bound_ctrl:1
	v_mov_b32_e32 v91, v90
	s_nop 1
	v_permlane16_swap_b32_e32 v90, v91
	s_and_saveexec_b64 s[24:25], s[2:3]
	v_add_f32_e32 v90, v90, v91
	ds_write_b32 v138, v90 offset:16
	s_or_b64 exec, exec, s[24:25]
	v_mul_f32_e32 v87, v87, v137
	v_fmac_f32_e32 v87, v86, v135
	v_fmac_f32_e32 v87, v88, v136
	v_fmac_f32_e32 v87, v89, v134
	s_nop 1
	v_add_f32_dpp v86, v87, v87 quad_perm:[1,0,3,2] row_mask:0xf bank_mask:0xf bound_ctrl:1
	s_nop 1
	v_add_f32_dpp v86, v86, v86 quad_perm:[2,3,0,1] row_mask:0xf bank_mask:0xf bound_ctrl:1
	s_nop 1
	v_add_f32_dpp v86, v86, v86 row_ror:4 row_mask:0xf bank_mask:0xf bound_ctrl:1
	s_nop 1
	v_add_f32_dpp v86, v86, v86 row_ror:8 row_mask:0xf bank_mask:0xf bound_ctrl:1
	v_mov_b32_e32 v87, v86
	s_nop 1
	v_permlane16_swap_b32_e32 v86, v87
	s_and_saveexec_b64 s[24:25], s[2:3]
	v_add_f32_e32 v86, v86, v87
	ds_write_b32 v138, v86 offset:20
	s_or_b64 exec, exec, s[24:25]
	v_mul_f32_e32 v83, v83, v137
	v_fmac_f32_e32 v83, v82, v135
	v_fmac_f32_e32 v83, v84, v136
	v_fmac_f32_e32 v83, v85, v134
	s_nop 1
	v_add_f32_dpp v82, v83, v83 quad_perm:[1,0,3,2] row_mask:0xf bank_mask:0xf bound_ctrl:1
	s_nop 1
	v_add_f32_dpp v82, v82, v82 quad_perm:[2,3,0,1] row_mask:0xf bank_mask:0xf bound_ctrl:1
	s_nop 1
	v_add_f32_dpp v82, v82, v82 row_ror:4 row_mask:0xf bank_mask:0xf bound_ctrl:1
	s_nop 1
	v_add_f32_dpp v82, v82, v82 row_ror:8 row_mask:0xf bank_mask:0xf bound_ctrl:1
	v_mov_b32_e32 v83, v82
	s_nop 1
	v_permlane16_swap_b32_e32 v82, v83
	s_and_saveexec_b64 s[24:25], s[2:3]
	v_add_f32_e32 v82, v82, v83
	ds_write_b32 v138, v82 offset:24
	s_or_b64 exec, exec, s[24:25]
	v_mul_f32_e32 v79, v79, v137
	v_fmac_f32_e32 v79, v78, v135
	v_fmac_f32_e32 v79, v80, v136
	v_fmac_f32_e32 v79, v81, v134
	s_nop 1
	v_add_f32_dpp v78, v79, v79 quad_perm:[1,0,3,2] row_mask:0xf bank_mask:0xf bound_ctrl:1
	s_nop 1
	v_add_f32_dpp v78, v78, v78 quad_perm:[2,3,0,1] row_mask:0xf bank_mask:0xf bound_ctrl:1
	s_nop 1
	v_add_f32_dpp v78, v78, v78 row_ror:4 row_mask:0xf bank_mask:0xf bound_ctrl:1
	s_nop 1
	v_add_f32_dpp v78, v78, v78 row_ror:8 row_mask:0xf bank_mask:0xf bound_ctrl:1
	v_mov_b32_e32 v79, v78
	s_nop 1
	v_permlane16_swap_b32_e32 v78, v79
	s_and_saveexec_b64 s[24:25], s[2:3]
	v_add_f32_e32 v78, v78, v79
	ds_write_b32 v138, v78 offset:28
	s_or_b64 exec, exec, s[24:25]
	v_mul_f32_e32 v75, v75, v137
	v_fmac_f32_e32 v75, v74, v135
	v_fmac_f32_e32 v75, v76, v136
	v_fmac_f32_e32 v75, v77, v134
	s_nop 1
	v_add_f32_dpp v74, v75, v75 quad_perm:[1,0,3,2] row_mask:0xf bank_mask:0xf bound_ctrl:1
	s_nop 1
	v_add_f32_dpp v74, v74, v74 quad_perm:[2,3,0,1] row_mask:0xf bank_mask:0xf bound_ctrl:1
	s_nop 1
	v_add_f32_dpp v74, v74, v74 row_ror:4 row_mask:0xf bank_mask:0xf bound_ctrl:1
	s_nop 1
	v_add_f32_dpp v74, v74, v74 row_ror:8 row_mask:0xf bank_mask:0xf bound_ctrl:1
	v_mov_b32_e32 v75, v74
	s_nop 1
	v_permlane16_swap_b32_e32 v74, v75
	s_and_saveexec_b64 s[24:25], s[2:3]
	v_add_f32_e32 v74, v74, v75
	ds_write_b32 v138, v74 offset:32
	s_or_b64 exec, exec, s[24:25]
	v_mul_f32_e32 v67, v67, v137
	v_fmac_f32_e32 v67, v66, v135
	v_fmac_f32_e32 v67, v68, v136
	v_fmac_f32_e32 v67, v69, v134
	s_nop 1
	v_add_f32_dpp v66, v67, v67 quad_perm:[1,0,3,2] row_mask:0xf bank_mask:0xf bound_ctrl:1
	s_nop 1
	v_add_f32_dpp v66, v66, v66 quad_perm:[2,3,0,1] row_mask:0xf bank_mask:0xf bound_ctrl:1
	s_nop 1
	v_add_f32_dpp v66, v66, v66 row_ror:4 row_mask:0xf bank_mask:0xf bound_ctrl:1
	s_nop 1
	v_add_f32_dpp v66, v66, v66 row_ror:8 row_mask:0xf bank_mask:0xf bound_ctrl:1
	v_mov_b32_e32 v67, v66
	s_nop 1
	v_permlane16_swap_b32_e32 v66, v67
	s_and_saveexec_b64 s[24:25], s[2:3]
	v_add_f32_e32 v66, v66, v67
	ds_write_b32 v138, v66 offset:36
	s_or_b64 exec, exec, s[24:25]
	v_mul_f32_e32 v63, v63, v137
	v_fmac_f32_e32 v63, v62, v135
	v_fmac_f32_e32 v63, v64, v136
	v_fmac_f32_e32 v63, v65, v134
	s_nop 1
	v_add_f32_dpp v62, v63, v63 quad_perm:[1,0,3,2] row_mask:0xf bank_mask:0xf bound_ctrl:1
	s_nop 1
	v_add_f32_dpp v62, v62, v62 quad_perm:[2,3,0,1] row_mask:0xf bank_mask:0xf bound_ctrl:1
	s_nop 1
	v_add_f32_dpp v62, v62, v62 row_ror:4 row_mask:0xf bank_mask:0xf bound_ctrl:1
	s_nop 1
	v_add_f32_dpp v62, v62, v62 row_ror:8 row_mask:0xf bank_mask:0xf bound_ctrl:1
	v_mov_b32_e32 v63, v62
	s_nop 1
	v_permlane16_swap_b32_e32 v62, v63
	s_and_saveexec_b64 s[24:25], s[2:3]
	v_add_f32_e32 v62, v62, v63
	ds_write_b32 v138, v62 offset:40
	s_or_b64 exec, exec, s[24:25]
	v_mul_f32_e32 v59, v59, v137
	v_fmac_f32_e32 v59, v58, v135
	v_fmac_f32_e32 v59, v60, v136
	v_fmac_f32_e32 v59, v61, v134
	s_nop 1
	v_add_f32_dpp v58, v59, v59 quad_perm:[1,0,3,2] row_mask:0xf bank_mask:0xf bound_ctrl:1
	s_nop 1
	v_add_f32_dpp v58, v58, v58 quad_perm:[2,3,0,1] row_mask:0xf bank_mask:0xf bound_ctrl:1
	s_nop 1
	v_add_f32_dpp v58, v58, v58 row_ror:4 row_mask:0xf bank_mask:0xf bound_ctrl:1
	s_nop 1
	v_add_f32_dpp v58, v58, v58 row_ror:8 row_mask:0xf bank_mask:0xf bound_ctrl:1
	v_mov_b32_e32 v59, v58
	s_nop 1
	v_permlane16_swap_b32_e32 v58, v59
	s_and_saveexec_b64 s[24:25], s[2:3]
	v_add_f32_e32 v58, v58, v59
	ds_write_b32 v138, v58 offset:44
	s_or_b64 exec, exec, s[24:25]
	v_mul_f32_e32 v55, v55, v137
	v_fmac_f32_e32 v55, v54, v135
	v_fmac_f32_e32 v55, v56, v136
	v_fmac_f32_e32 v55, v57, v134
	s_nop 1
	v_add_f32_dpp v54, v55, v55 quad_perm:[1,0,3,2] row_mask:0xf bank_mask:0xf bound_ctrl:1
	s_nop 1
	v_add_f32_dpp v54, v54, v54 quad_perm:[2,3,0,1] row_mask:0xf bank_mask:0xf bound_ctrl:1
	s_nop 1
	v_add_f32_dpp v54, v54, v54 row_ror:4 row_mask:0xf bank_mask:0xf bound_ctrl:1
	s_nop 1
	v_add_f32_dpp v54, v54, v54 row_ror:8 row_mask:0xf bank_mask:0xf bound_ctrl:1
	v_mov_b32_e32 v55, v54
	s_nop 1
	v_permlane16_swap_b32_e32 v54, v55
	s_and_saveexec_b64 s[24:25], s[2:3]
	v_add_f32_e32 v54, v54, v55
	ds_write_b32 v138, v54 offset:48
	s_or_b64 exec, exec, s[24:25]
	v_mul_f32_e32 v51, v51, v137
	v_fmac_f32_e32 v51, v50, v135
	v_fmac_f32_e32 v51, v52, v136
	v_fmac_f32_e32 v51, v53, v134
	s_nop 1
	v_add_f32_dpp v50, v51, v51 quad_perm:[1,0,3,2] row_mask:0xf bank_mask:0xf bound_ctrl:1
	s_nop 1
	v_add_f32_dpp v50, v50, v50 quad_perm:[2,3,0,1] row_mask:0xf bank_mask:0xf bound_ctrl:1
	s_nop 1
	v_add_f32_dpp v50, v50, v50 row_ror:4 row_mask:0xf bank_mask:0xf bound_ctrl:1
	s_nop 1
	v_add_f32_dpp v50, v50, v50 row_ror:8 row_mask:0xf bank_mask:0xf bound_ctrl:1
	v_mov_b32_e32 v51, v50
	s_nop 1
	v_permlane16_swap_b32_e32 v50, v51
	s_and_saveexec_b64 s[24:25], s[2:3]
	v_add_f32_e32 v50, v50, v51
	ds_write_b32 v138, v50 offset:52
	s_or_b64 exec, exec, s[24:25]
	v_mul_f32_e32 v47, v47, v137
	v_fmac_f32_e32 v47, v46, v135
	v_fmac_f32_e32 v47, v48, v136
	v_fmac_f32_e32 v47, v49, v134
	s_nop 1
	v_add_f32_dpp v46, v47, v47 quad_perm:[1,0,3,2] row_mask:0xf bank_mask:0xf bound_ctrl:1
	s_nop 1
	v_add_f32_dpp v46, v46, v46 quad_perm:[2,3,0,1] row_mask:0xf bank_mask:0xf bound_ctrl:1
	s_nop 1
	v_add_f32_dpp v46, v46, v46 row_ror:4 row_mask:0xf bank_mask:0xf bound_ctrl:1
	s_nop 1
	v_add_f32_dpp v46, v46, v46 row_ror:8 row_mask:0xf bank_mask:0xf bound_ctrl:1
	v_mov_b32_e32 v47, v46
	s_nop 1
	v_permlane16_swap_b32_e32 v46, v47
	s_and_saveexec_b64 s[24:25], s[2:3]
	v_add_f32_e32 v46, v46, v47
	ds_write_b32 v138, v46 offset:56
	s_or_b64 exec, exec, s[24:25]
	v_mul_f32_e32 v43, v43, v137
	v_fmac_f32_e32 v43, v42, v135
	v_fmac_f32_e32 v43, v44, v136
	v_fmac_f32_e32 v43, v45, v134
	s_nop 1
	v_add_f32_dpp v42, v43, v43 quad_perm:[1,0,3,2] row_mask:0xf bank_mask:0xf bound_ctrl:1
	s_nop 1
	v_add_f32_dpp v42, v42, v42 quad_perm:[2,3,0,1] row_mask:0xf bank_mask:0xf bound_ctrl:1
	s_nop 1
	v_add_f32_dpp v42, v42, v42 row_ror:4 row_mask:0xf bank_mask:0xf bound_ctrl:1
	s_nop 1
	v_add_f32_dpp v42, v42, v42 row_ror:8 row_mask:0xf bank_mask:0xf bound_ctrl:1
	v_mov_b32_e32 v43, v42
	s_nop 1
	v_permlane16_swap_b32_e32 v42, v43
	s_and_saveexec_b64 s[24:25], s[2:3]
	v_add_f32_e32 v42, v42, v43
	ds_write_b32 v138, v42 offset:60
	s_or_b64 exec, exec, s[24:25]
	s_add_u32 s24, s18, s6
	s_addc_u32 s25, s19, s7
	v_lshl_add_u64 v[130:131], s[24:25], 0, v[106:107]
	v_add_co_u32_e32 v42, vcc, 0x1000, v130
	global_load_dwordx4 v[106:109], v[130:131], off nt
	global_load_dwordx4 v[94:97], v[130:131], off offset:2048 nt
	v_addc_co_u32_e32 v43, vcc, 0, v131, vcc
	global_load_dwordx4 v[102:105], v[42:43], off nt
	global_load_dwordx4 v[78:81], v[42:43], off offset:2048 nt
	v_add_co_u32_e32 v42, vcc, 0x2000, v130
	s_nop 1
	v_addc_co_u32_e32 v43, vcc, 0, v131, vcc
	global_load_dwordx4 v[98:101], v[42:43], off nt
	global_load_dwordx4 v[82:85], v[42:43], off offset:2048 nt
	v_add_co_u32_e32 v42, vcc, 0x3000, v130
	s_nop 1
	v_addc_co_u32_e32 v43, vcc, 0, v131, vcc
	global_load_dwordx4 v[90:93], v[42:43], off nt
	global_load_dwordx4 v[58:61], v[42:43], off offset:2048 nt
	v_add_co_u32_e32 v42, vcc, 0x4000, v130
	s_nop 1
	v_addc_co_u32_e32 v43, vcc, 0, v131, vcc
	global_load_dwordx4 v[86:89], v[42:43], off nt
	global_load_dwordx4 v[62:65], v[42:43], off offset:2048 nt
	v_add_co_u32_e32 v42, vcc, 0x5000, v130
	s_nop 1
	v_addc_co_u32_e32 v43, vcc, 0, v131, vcc
	global_load_dwordx4 v[74:77], v[42:43], off nt
	global_load_dwordx4 v[46:49], v[42:43], off offset:2048 nt
	v_add_co_u32_e32 v42, vcc, 0x6000, v130
	s_nop 1
	v_addc_co_u32_e32 v43, vcc, 0, v131, vcc
	global_load_dwordx4 v[66:69], v[42:43], off nt
	global_load_dwordx4 v[50:53], v[42:43], off offset:2048 nt
	v_add_co_u32_e32 v42, vcc, 0x7000, v130
	s_nop 1
	v_addc_co_u32_e32 v43, vcc, 0, v131, vcc
	global_load_dwordx4 v[54:57], v[42:43], off nt
	s_nop 0
	global_load_dwordx4 v[42:45], v[42:43], off offset:2048 nt
	v_mul_f32_e32 v127, v127, v137
	v_fmac_f32_e32 v127, v126, v135
	v_fmac_f32_e32 v127, v128, v136
	v_fmac_f32_e32 v127, v129, v134
	s_nop 1
	v_add_f32_dpp v126, v127, v127 quad_perm:[1,0,3,2] row_mask:0xf bank_mask:0xf bound_ctrl:1
	s_nop 1
	v_add_f32_dpp v126, v126, v126 quad_perm:[2,3,0,1] row_mask:0xf bank_mask:0xf bound_ctrl:1
	s_nop 1
	v_add_f32_dpp v126, v126, v126 row_ror:4 row_mask:0xf bank_mask:0xf bound_ctrl:1
	s_nop 1
	v_add_f32_dpp v126, v126, v126 row_ror:8 row_mask:0xf bank_mask:0xf bound_ctrl:1
	v_mov_b32_e32 v127, v126
	s_nop 1
	v_permlane16_swap_b32_e32 v126, v127
	s_and_saveexec_b64 s[24:25], s[2:3]
	v_add_f32_e32 v126, v126, v127
	ds_write_b32 v138, v126 offset:64
	s_or_b64 exec, exec, s[24:25]
	v_mul_f32_e32 v123, v123, v137
	v_fmac_f32_e32 v123, v122, v135
	v_fmac_f32_e32 v123, v124, v136
	v_fmac_f32_e32 v123, v125, v134
	s_nop 1
	v_add_f32_dpp v122, v123, v123 quad_perm:[1,0,3,2] row_mask:0xf bank_mask:0xf bound_ctrl:1
	s_nop 1
	v_add_f32_dpp v122, v122, v122 quad_perm:[2,3,0,1] row_mask:0xf bank_mask:0xf bound_ctrl:1
	s_nop 1
	v_add_f32_dpp v122, v122, v122 row_ror:4 row_mask:0xf bank_mask:0xf bound_ctrl:1
	s_nop 1
	v_add_f32_dpp v122, v122, v122 row_ror:8 row_mask:0xf bank_mask:0xf bound_ctrl:1
	v_mov_b32_e32 v123, v122
	s_nop 1
	v_permlane16_swap_b32_e32 v122, v123
	s_and_saveexec_b64 s[24:25], s[2:3]
	v_add_f32_e32 v122, v122, v123
	ds_write_b32 v138, v122 offset:68
	s_or_b64 exec, exec, s[24:25]
	v_mul_f32_e32 v119, v119, v137
	v_fmac_f32_e32 v119, v118, v135
	v_fmac_f32_e32 v119, v120, v136
	v_fmac_f32_e32 v119, v121, v134
	s_nop 1
	v_add_f32_dpp v118, v119, v119 quad_perm:[1,0,3,2] row_mask:0xf bank_mask:0xf bound_ctrl:1
	s_nop 1
	v_add_f32_dpp v118, v118, v118 quad_perm:[2,3,0,1] row_mask:0xf bank_mask:0xf bound_ctrl:1
	s_nop 1
	v_add_f32_dpp v118, v118, v118 row_ror:4 row_mask:0xf bank_mask:0xf bound_ctrl:1
	s_nop 1
	v_add_f32_dpp v118, v118, v118 row_ror:8 row_mask:0xf bank_mask:0xf bound_ctrl:1
	v_mov_b32_e32 v119, v118
	s_nop 1
	v_permlane16_swap_b32_e32 v118, v119
	s_and_saveexec_b64 s[24:25], s[2:3]
	v_add_f32_e32 v118, v118, v119
	ds_write_b32 v138, v118 offset:72
	s_or_b64 exec, exec, s[24:25]
	v_mul_f32_e32 v115, v115, v137
	v_fmac_f32_e32 v115, v114, v135
	v_fmac_f32_e32 v115, v116, v136
	v_fmac_f32_e32 v115, v117, v134
	s_nop 1
	v_add_f32_dpp v114, v115, v115 quad_perm:[1,0,3,2] row_mask:0xf bank_mask:0xf bound_ctrl:1
	s_nop 1
	v_add_f32_dpp v114, v114, v114 quad_perm:[2,3,0,1] row_mask:0xf bank_mask:0xf bound_ctrl:1
	s_nop 1
	v_add_f32_dpp v114, v114, v114 row_ror:4 row_mask:0xf bank_mask:0xf bound_ctrl:1
	s_nop 1
	v_add_f32_dpp v114, v114, v114 row_ror:8 row_mask:0xf bank_mask:0xf bound_ctrl:1
	v_mov_b32_e32 v115, v114
	s_nop 1
	v_permlane16_swap_b32_e32 v114, v115
	s_and_saveexec_b64 s[24:25], s[2:3]
	v_add_f32_e32 v114, v114, v115
	ds_write_b32 v138, v114 offset:76
	s_or_b64 exec, exec, s[24:25]
	v_mul_f32_e32 v111, v111, v137
	v_fmac_f32_e32 v111, v110, v135
	v_fmac_f32_e32 v111, v112, v136
	v_fmac_f32_e32 v111, v113, v134
	s_nop 1
	v_add_f32_dpp v110, v111, v111 quad_perm:[1,0,3,2] row_mask:0xf bank_mask:0xf bound_ctrl:1
	s_nop 1
	v_add_f32_dpp v110, v110, v110 quad_perm:[2,3,0,1] row_mask:0xf bank_mask:0xf bound_ctrl:1
	s_nop 1
	v_add_f32_dpp v110, v110, v110 row_ror:4 row_mask:0xf bank_mask:0xf bound_ctrl:1
	s_nop 1
	v_add_f32_dpp v110, v110, v110 row_ror:8 row_mask:0xf bank_mask:0xf bound_ctrl:1
	v_mov_b32_e32 v111, v110
	s_nop 1
	v_permlane16_swap_b32_e32 v110, v111
	s_and_saveexec_b64 s[24:25], s[2:3]
	v_add_f32_e32 v110, v110, v111
	ds_write_b32 v138, v110 offset:80
	s_or_b64 exec, exec, s[24:25]
	v_mul_f32_e32 v71, v71, v137
	v_fmac_f32_e32 v71, v70, v135
	v_fmac_f32_e32 v71, v72, v136
	v_fmac_f32_e32 v71, v73, v134
	s_nop 1
	v_add_f32_dpp v70, v71, v71 quad_perm:[1,0,3,2] row_mask:0xf bank_mask:0xf bound_ctrl:1
	s_nop 1
	v_add_f32_dpp v70, v70, v70 quad_perm:[2,3,0,1] row_mask:0xf bank_mask:0xf bound_ctrl:1
	s_nop 1
	v_add_f32_dpp v70, v70, v70 row_ror:4 row_mask:0xf bank_mask:0xf bound_ctrl:1
	s_nop 1
	v_add_f32_dpp v70, v70, v70 row_ror:8 row_mask:0xf bank_mask:0xf bound_ctrl:1
	v_mov_b32_e32 v71, v70
	s_nop 1
	v_permlane16_swap_b32_e32 v70, v71
	s_and_saveexec_b64 s[24:25], s[2:3]
	v_add_f32_e32 v70, v70, v71
	ds_write_b32 v138, v70 offset:84
	s_or_b64 exec, exec, s[24:25]
	v_mul_f32_e32 v39, v39, v137
	v_fmac_f32_e32 v39, v38, v135
	v_fmac_f32_e32 v39, v40, v136
	v_fmac_f32_e32 v39, v41, v134
	s_nop 1
	v_add_f32_dpp v38, v39, v39 quad_perm:[1,0,3,2] row_mask:0xf bank_mask:0xf bound_ctrl:1
	s_nop 1
	v_add_f32_dpp v38, v38, v38 quad_perm:[2,3,0,1] row_mask:0xf bank_mask:0xf bound_ctrl:1
	s_nop 1
	v_add_f32_dpp v38, v38, v38 row_ror:4 row_mask:0xf bank_mask:0xf bound_ctrl:1
	s_nop 1
	v_add_f32_dpp v38, v38, v38 row_ror:8 row_mask:0xf bank_mask:0xf bound_ctrl:1
	v_mov_b32_e32 v39, v38
	s_nop 1
	v_permlane16_swap_b32_e32 v38, v39
	s_and_saveexec_b64 s[24:25], s[2:3]
	v_add_f32_e32 v38, v38, v39
	ds_write_b32 v138, v38 offset:88
	s_or_b64 exec, exec, s[24:25]
	v_mul_f32_e32 v35, v35, v137
	v_fmac_f32_e32 v35, v34, v135
	v_fmac_f32_e32 v35, v36, v136
	v_fmac_f32_e32 v35, v37, v134
	s_nop 1
	v_add_f32_dpp v34, v35, v35 quad_perm:[1,0,3,2] row_mask:0xf bank_mask:0xf bound_ctrl:1
	s_nop 1
	v_add_f32_dpp v34, v34, v34 quad_perm:[2,3,0,1] row_mask:0xf bank_mask:0xf bound_ctrl:1
	s_nop 1
	v_add_f32_dpp v34, v34, v34 row_ror:4 row_mask:0xf bank_mask:0xf bound_ctrl:1
	s_nop 1
	v_add_f32_dpp v34, v34, v34 row_ror:8 row_mask:0xf bank_mask:0xf bound_ctrl:1
	v_mov_b32_e32 v35, v34
	s_nop 1
	v_permlane16_swap_b32_e32 v34, v35
	s_and_saveexec_b64 s[24:25], s[2:3]
	v_add_f32_e32 v34, v34, v35
	ds_write_b32 v138, v34 offset:92
	s_or_b64 exec, exec, s[24:25]
	v_mul_f32_e32 v31, v31, v137
	v_fmac_f32_e32 v31, v30, v135
	v_fmac_f32_e32 v31, v32, v136
	v_fmac_f32_e32 v31, v33, v134
	s_nop 1
	v_add_f32_dpp v30, v31, v31 quad_perm:[1,0,3,2] row_mask:0xf bank_mask:0xf bound_ctrl:1
	s_nop 1
	v_add_f32_dpp v30, v30, v30 quad_perm:[2,3,0,1] row_mask:0xf bank_mask:0xf bound_ctrl:1
	s_nop 1
	v_add_f32_dpp v30, v30, v30 row_ror:4 row_mask:0xf bank_mask:0xf bound_ctrl:1
	s_nop 1
	v_add_f32_dpp v30, v30, v30 row_ror:8 row_mask:0xf bank_mask:0xf bound_ctrl:1
	v_mov_b32_e32 v31, v30
	s_nop 1
	v_permlane16_swap_b32_e32 v30, v31
	s_and_saveexec_b64 s[24:25], s[2:3]
	v_add_f32_e32 v30, v30, v31
	ds_write_b32 v138, v30 offset:96
	s_or_b64 exec, exec, s[24:25]
	v_mul_f32_e32 v27, v27, v137
	v_fmac_f32_e32 v27, v26, v135
	v_fmac_f32_e32 v27, v28, v136
	v_fmac_f32_e32 v27, v29, v134
	s_nop 1
	v_add_f32_dpp v26, v27, v27 quad_perm:[1,0,3,2] row_mask:0xf bank_mask:0xf bound_ctrl:1
	s_nop 1
	v_add_f32_dpp v26, v26, v26 quad_perm:[2,3,0,1] row_mask:0xf bank_mask:0xf bound_ctrl:1
	s_nop 1
	v_add_f32_dpp v26, v26, v26 row_ror:4 row_mask:0xf bank_mask:0xf bound_ctrl:1
	s_nop 1
	v_add_f32_dpp v26, v26, v26 row_ror:8 row_mask:0xf bank_mask:0xf bound_ctrl:1
	v_mov_b32_e32 v27, v26
	s_nop 1
	v_permlane16_swap_b32_e32 v26, v27
	s_and_saveexec_b64 s[24:25], s[2:3]
	v_add_f32_e32 v26, v26, v27
	ds_write_b32 v138, v26 offset:100
	s_or_b64 exec, exec, s[24:25]
	v_mul_f32_e32 v23, v23, v137
	v_fmac_f32_e32 v23, v22, v135
	v_fmac_f32_e32 v23, v24, v136
	v_fmac_f32_e32 v23, v25, v134
	s_nop 1
	v_add_f32_dpp v22, v23, v23 quad_perm:[1,0,3,2] row_mask:0xf bank_mask:0xf bound_ctrl:1
	s_nop 1
	v_add_f32_dpp v22, v22, v22 quad_perm:[2,3,0,1] row_mask:0xf bank_mask:0xf bound_ctrl:1
	s_nop 1
	v_add_f32_dpp v22, v22, v22 row_ror:4 row_mask:0xf bank_mask:0xf bound_ctrl:1
	s_nop 1
	v_add_f32_dpp v22, v22, v22 row_ror:8 row_mask:0xf bank_mask:0xf bound_ctrl:1
	v_mov_b32_e32 v23, v22
	s_nop 1
	v_permlane16_swap_b32_e32 v22, v23
	s_and_saveexec_b64 s[24:25], s[2:3]
	v_add_f32_e32 v22, v22, v23
	ds_write_b32 v138, v22 offset:104
	s_or_b64 exec, exec, s[24:25]
	v_mul_f32_e32 v19, v19, v137
	v_fmac_f32_e32 v19, v18, v135
	v_fmac_f32_e32 v19, v20, v136
	v_fmac_f32_e32 v19, v21, v134
	s_nop 1
	v_add_f32_dpp v18, v19, v19 quad_perm:[1,0,3,2] row_mask:0xf bank_mask:0xf bound_ctrl:1
	s_nop 1
	v_add_f32_dpp v18, v18, v18 quad_perm:[2,3,0,1] row_mask:0xf bank_mask:0xf bound_ctrl:1
	s_nop 1
	v_add_f32_dpp v18, v18, v18 row_ror:4 row_mask:0xf bank_mask:0xf bound_ctrl:1
	s_nop 1
	v_add_f32_dpp v18, v18, v18 row_ror:8 row_mask:0xf bank_mask:0xf bound_ctrl:1
	v_mov_b32_e32 v19, v18
	s_nop 1
	v_permlane16_swap_b32_e32 v18, v19
	s_and_saveexec_b64 s[24:25], s[2:3]
	v_add_f32_e32 v18, v18, v19
	ds_write_b32 v138, v18 offset:108
	s_or_b64 exec, exec, s[24:25]
	v_mul_f32_e32 v15, v15, v137
	v_fmac_f32_e32 v15, v14, v135
	v_fmac_f32_e32 v15, v16, v136
	v_fmac_f32_e32 v15, v17, v134
	s_nop 1
	v_add_f32_dpp v14, v15, v15 quad_perm:[1,0,3,2] row_mask:0xf bank_mask:0xf bound_ctrl:1
	s_nop 1
	v_add_f32_dpp v14, v14, v14 quad_perm:[2,3,0,1] row_mask:0xf bank_mask:0xf bound_ctrl:1
	s_nop 1
	v_add_f32_dpp v14, v14, v14 row_ror:4 row_mask:0xf bank_mask:0xf bound_ctrl:1
	s_nop 1
	v_add_f32_dpp v14, v14, v14 row_ror:8 row_mask:0xf bank_mask:0xf bound_ctrl:1
	v_mov_b32_e32 v15, v14
	s_nop 1
	v_permlane16_swap_b32_e32 v14, v15
	s_and_saveexec_b64 s[24:25], s[2:3]
	v_add_f32_e32 v14, v14, v15
	ds_write_b32 v138, v14 offset:112
	s_or_b64 exec, exec, s[24:25]
	v_mul_f32_e32 v11, v11, v137
	v_fmac_f32_e32 v11, v10, v135
	v_fmac_f32_e32 v11, v12, v136
	v_fmac_f32_e32 v11, v13, v134
	s_nop 1
	v_add_f32_dpp v10, v11, v11 quad_perm:[1,0,3,2] row_mask:0xf bank_mask:0xf bound_ctrl:1
	s_nop 1
	v_add_f32_dpp v10, v10, v10 quad_perm:[2,3,0,1] row_mask:0xf bank_mask:0xf bound_ctrl:1
	s_nop 1
	v_add_f32_dpp v10, v10, v10 row_ror:4 row_mask:0xf bank_mask:0xf bound_ctrl:1
	s_nop 1
	v_add_f32_dpp v10, v10, v10 row_ror:8 row_mask:0xf bank_mask:0xf bound_ctrl:1
	v_mov_b32_e32 v11, v10
	s_nop 1
	v_permlane16_swap_b32_e32 v10, v11
	s_and_saveexec_b64 s[24:25], s[2:3]
	v_add_f32_e32 v10, v10, v11
	ds_write_b32 v138, v10 offset:116
	s_or_b64 exec, exec, s[24:25]
	v_mul_f32_e32 v7, v7, v137
	v_fmac_f32_e32 v7, v6, v135
	v_fmac_f32_e32 v7, v8, v136
	v_fmac_f32_e32 v7, v9, v134
	s_nop 1
	v_add_f32_dpp v6, v7, v7 quad_perm:[1,0,3,2] row_mask:0xf bank_mask:0xf bound_ctrl:1
	s_nop 1
	v_add_f32_dpp v6, v6, v6 quad_perm:[2,3,0,1] row_mask:0xf bank_mask:0xf bound_ctrl:1
	s_nop 1
	v_add_f32_dpp v6, v6, v6 row_ror:4 row_mask:0xf bank_mask:0xf bound_ctrl:1
	s_nop 1
	v_add_f32_dpp v6, v6, v6 row_ror:8 row_mask:0xf bank_mask:0xf bound_ctrl:1
	v_mov_b32_e32 v7, v6
	s_nop 1
	v_permlane16_swap_b32_e32 v6, v7
	s_and_saveexec_b64 s[24:25], s[2:3]
	v_add_f32_e32 v6, v6, v7
	ds_write_b32 v138, v6 offset:120
	s_or_b64 exec, exec, s[24:25]
	s_waitcnt vmcnt(16)
	v_mul_f32_e32 v3, v3, v137
	v_fmac_f32_e32 v3, v2, v135
	v_fmac_f32_e32 v3, v4, v136
	v_fmac_f32_e32 v3, v5, v134
	s_nop 1
	v_add_f32_dpp v2, v3, v3 quad_perm:[1,0,3,2] row_mask:0xf bank_mask:0xf bound_ctrl:1
	s_nop 1
	v_add_f32_dpp v2, v2, v2 quad_perm:[2,3,0,1] row_mask:0xf bank_mask:0xf bound_ctrl:1
	s_nop 1
	v_add_f32_dpp v2, v2, v2 row_ror:4 row_mask:0xf bank_mask:0xf bound_ctrl:1
	s_nop 1
	v_add_f32_dpp v2, v2, v2 row_ror:8 row_mask:0xf bank_mask:0xf bound_ctrl:1
	v_mov_b32_e32 v3, v2
	s_nop 1
	v_permlane16_swap_b32_e32 v2, v3
	s_and_saveexec_b64 s[24:25], s[2:3]
	v_add_f32_e32 v2, v2, v3
	ds_write_b32 v138, v2 offset:124
	s_or_b64 exec, exec, s[24:25]
	v_lshlrev_b32_e32 v134, 2, v132
	v_add_co_u32_e32 v2, vcc, 0x8000, v130
	s_nop 1
	v_addc_co_u32_e32 v3, vcc, 0, v131, vcc
	global_load_dwordx4 v[70:73], v[2:3], off nt
	global_load_dwordx4 v[38:41], v[2:3], off offset:2048 nt
	v_add_co_u32_e32 v2, vcc, 0x9000, v130
	s_nop 1
	v_addc_co_u32_e32 v3, vcc, 0, v131, vcc
	global_load_dwordx4 v[118:121], v[2:3], off nt
	global_load_dwordx4 v[110:113], v[2:3], off offset:2048 nt
	v_add_co_u32_e32 v2, vcc, 0xa000, v130
	s_nop 1
	v_addc_co_u32_e32 v3, vcc, 0, v131, vcc
	global_load_dwordx4 v[126:129], v[2:3], off nt
	global_load_dwordx4 v[114:117], v[2:3], off offset:2048 nt
	v_add_co_u32_e32 v2, vcc, 0xb000, v130
	s_nop 1
	v_addc_co_u32_e32 v3, vcc, 0, v131, vcc
	global_load_dwordx4 v[122:125], v[2:3], off nt
	global_load_dwordx4 v[34:37], v[2:3], off offset:2048 nt
	v_add_co_u32_e32 v2, vcc, 0xc000, v130
	s_nop 1
	v_addc_co_u32_e32 v3, vcc, 0, v131, vcc
	v_add_co_u32_e32 v6, vcc, 0xd000, v130
	global_load_dwordx4 v[10:13], v[2:3], off nt
	s_nop 0
	global_load_dwordx4 v[2:5], v[2:3], off offset:2048 nt
	v_addc_co_u32_e32 v7, vcc, 0, v131, vcc
	global_load_dwordx4 v[22:25], v[6:7], off nt
	global_load_dwordx4 v[14:17], v[6:7], off offset:2048 nt
	v_add_co_u32_e32 v6, vcc, 0xe000, v130
	s_nop 1
	v_addc_co_u32_e32 v7, vcc, 0, v131, vcc
	global_load_dwordx4 v[30:33], v[6:7], off nt
	global_load_dwordx4 v[18:21], v[6:7], off offset:2048 nt
	v_add_co_u32_e32 v6, vcc, 0xf000, v130
	s_nop 1
	v_addc_co_u32_e32 v7, vcc, 0, v131, vcc
	global_load_dwordx4 v[26:29], v[6:7], off nt
	s_nop 0
	global_load_dwordx4 v[6:9], v[6:7], off offset:2048 nt
	s_waitcnt lgkmcnt(0)
	s_barrier
	s_lshl_b32 s23, s47, 10
	s_cmp_gt_i32 s47, 1
	s_cbranch_scc1 .LBB0_622
	s_add_i32 s24, s23, 0
	v_lshl_add_u32 v135, v134, 2, s24
	ds_read_b128 v[136:139], v135
	v_cmp_eq_u32_e32 vcc, 0, v132
	s_waitcnt lgkmcnt(0)
	v_max_f32_e32 v130, v139, v139
	v_max_f32_e32 v131, v138, v138
	v_max_f32_e32 v130, v131, v130
	v_max3_f32 v130, v136, v137, v130
	s_nop 1
	v_mov_b32_dpp v131, v130 quad_perm:[1,0,3,2] row_mask:0xf bank_mask:0xf bound_ctrl:1
	v_max_f32_e32 v131, v131, v131
	v_max_f32_e32 v130, v130, v131
	s_nop 1
	v_mov_b32_dpp v131, v130 quad_perm:[2,3,0,1] row_mask:0xf bank_mask:0xf bound_ctrl:1
	v_max_f32_e32 v131, v131, v131
	v_max_f32_e32 v130, v130, v131
	s_nop 1
	v_mov_b32_dpp v131, v130 row_ror:4 row_mask:0xf bank_mask:0xf bound_ctrl:1
	v_max_f32_e32 v131, v131, v131
	v_max_f32_e32 v130, v130, v131
	s_nop 1
	v_mov_b32_dpp v131, v130 row_ror:8 row_mask:0xf bank_mask:0xf bound_ctrl:1
	v_max_f32_e32 v131, v131, v131
	v_max_f32_e32 v130, v130, v131
	v_mov_b32_e32 v131, v130
	s_nop 1
	v_permlane16_swap_b32_e32 v130, v131
	v_max_f32_e32 v131, v131, v131
	v_max_f32_e32 v130, v130, v130
	v_max_f32_e32 v130, v130, v131
	v_mov_b32_e32 v131, v130
	s_nop 1
	v_permlane32_swap_b32_e32 v130, v131
	v_max_f32_e32 v131, v131, v131
	v_max_f32_e32 v130, v130, v130
	v_max_f32_e32 v130, v130, v131
	v_sub_f32_e32 v131, v136, v130
	v_exp_f32_e32 v136, v131
	v_sub_f32_e32 v131, v137, v130
	v_exp_f32_e32 v137, v131
	v_sub_f32_e32 v131, v138, v130
	v_exp_f32_e32 v138, v131
	v_sub_f32_e32 v130, v139, v130
	v_exp_f32_e32 v139, v130
	v_add_f32_e32 v130, v136, v137
	v_add_f32_e32 v130, v138, v130
	v_add_f32_e32 v130, v139, v130
	ds_write_b128 v135, v[136:139]
	s_nop 0
	v_add_f32_dpp v130, v130, v130 quad_perm:[1,0,3,2] row_mask:0xf bank_mask:0xf bound_ctrl:1
	s_nop 1
	v_add_f32_dpp v130, v130, v130 quad_perm:[2,3,0,1] row_mask:0xf bank_mask:0xf bound_ctrl:1
	s_nop 1
	v_add_f32_dpp v130, v130, v130 row_ror:4 row_mask:0xf bank_mask:0xf bound_ctrl:1
	s_nop 1
	v_add_f32_dpp v130, v130, v130 row_ror:8 row_mask:0xf bank_mask:0xf bound_ctrl:1
	v_mov_b32_e32 v131, v130
	s_nop 1
	v_permlane16_swap_b32_e32 v130, v131
	v_add_f32_e32 v130, v130, v131
	v_mov_b32_e32 v131, v130
	s_nop 1
	v_permlane32_swap_b32_e32 v130, v131
	s_and_saveexec_b64 s[2:3], vcc
	s_cbranch_execz .LBB0_621
	v_add_f32_e32 v130, v130, v131
	v_div_scale_f32 v131, s[48:49], v130, v130, 1.0
	v_rcp_f32_e32 v132, v131
	v_div_scale_f32 v135, vcc, 1.0, v130, 1.0
	s_mulk_i32 s47, 0xfc04
	v_fma_f32 v136, -v131, v132, 1.0
	v_fmac_f32_e32 v132, v136, v132
	v_mul_f32_e32 v136, v135, v132
	v_fma_f32 v137, -v131, v136, v135
	v_fmac_f32_e32 v136, v137, v132
	v_fma_f32 v131, -v131, v136, v135
	v_div_fmas_f32 v131, v131, v132, v136
	s_add_i32 s24, s24, s47
	v_div_fixup_f32 v130, v131, v130, 1.0
	v_mov_b32_e32 v131, s24
	ds_write_b32 v131, v130 offset:2048

.LBB0_812:
	v_mov_b32_e32 v1, v0
	s_nop 0
	v_readfirstlane_b32 s2, v1
	s_ashr_i32 s43, s2, 6
	s_lshl_b32 s18, s43, 5
	s_ashr_i32 s19, s18, 31
	v_and_b32_e32 v132, 63, v1
	s_lshl_b64 s[2:3], s[18:19], 11
	s_waitcnt vmcnt(0)
	v_lshl_or_b32 v106, v132, 4, s2
	s_add_u32 s2, s82, s6
	v_lshlrev_b32_e32 v2, 3, v132
	v_mov_b32_e32 v107, s3
	s_addc_u32 s3, s83, s7
	global_load_dwordx2 v[108:109], v2, s[14:15]
	v_lshl_add_u64 v[2:3], s[2:3], 0, v[106:107]
	v_add_co_u32_e32 v4, vcc, s22, v2
	global_load_dwordx4 v[138:141], v[2:3], off offset:1024 nt
	global_load_dwordx4 v[102:105], v[2:3], off offset:3072 nt
	v_addc_co_u32_e32 v5, vcc, 0, v3, vcc
	global_load_dwordx4 v[98:101], v[4:5], off offset:1024 nt
	global_load_dwordx4 v[94:97], v[4:5], off offset:3072 nt
	v_add_co_u32_e32 v4, vcc, s23, v2
	v_addc_co_u32_e32 v5, vcc, 0, v3, vcc
	global_load_dwordx4 v[90:93], v[4:5], off offset:1024 nt
	global_load_dwordx4 v[86:89], v[4:5], off offset:3072 nt
	v_add_co_u32_e32 v4, vcc, s24, v2
	s_nop 0
	v_addc_co_u32_e32 v5, vcc, 0, v3, vcc
	global_load_dwordx4 v[82:85], v[4:5], off offset:1024 nt
	global_load_dwordx4 v[78:81], v[4:5], off offset:3072 nt
	v_add_co_u32_e32 v4, vcc, s25, v2
	s_nop 0
	v_addc_co_u32_e32 v5, vcc, 0, v3, vcc
	global_load_dwordx4 v[74:77], v[4:5], off offset:1024 nt
	global_load_dwordx4 v[70:73], v[4:5], off offset:3072 nt
	v_add_co_u32_e32 v4, vcc, s28, v2
	s_nop 0
	v_addc_co_u32_e32 v5, vcc, 0, v3, vcc
	global_load_dwordx4 v[66:69], v[4:5], off offset:1024 nt
	global_load_dwordx4 v[62:65], v[4:5], off offset:3072 nt
	v_add_co_u32_e32 v4, vcc, s29, v2
	s_nop 1
	v_addc_co_u32_e32 v5, vcc, 0, v3, vcc
	global_load_dwordx4 v[58:61], v[4:5], off offset:1024 nt
	global_load_dwordx4 v[54:57], v[4:5], off offset:3072 nt
	v_add_co_u32_e32 v4, vcc, s30, v2
	s_nop 1
	v_addc_co_u32_e32 v5, vcc, 0, v3, vcc
	global_load_dwordx4 v[50:53], v[4:5], off offset:1024 nt
	global_load_dwordx4 v[46:49], v[4:5], off offset:3072 nt
	v_add_co_u32_e32 v4, vcc, s31, v2
	s_nop 1
	v_addc_co_u32_e32 v5, vcc, 0, v3, vcc
	global_load_dwordx4 v[126:129], v[4:5], off offset:1024 nt
	global_load_dwordx4 v[122:125], v[4:5], off offset:3072 nt
	v_add_co_u32_e32 v4, vcc, s33, v2
	s_nop 1
	v_addc_co_u32_e32 v5, vcc, 0, v3, vcc
	global_load_dwordx4 v[118:121], v[4:5], off offset:1024 nt
	global_load_dwordx4 v[114:117], v[4:5], off offset:3072 nt
	v_add_co_u32_e32 v4, vcc, s36, v2
	s_nop 1
	v_addc_co_u32_e32 v5, vcc, 0, v3, vcc
	global_load_dwordx4 v[110:113], v[4:5], off offset:1024 nt
	global_load_dwordx4 v[42:45], v[4:5], off offset:3072 nt
	v_add_co_u32_e32 v4, vcc, s37, v2
	s_nop 1
	v_addc_co_u32_e32 v5, vcc, 0, v3, vcc
	global_load_dwordx4 v[38:41], v[4:5], off offset:1024 nt
	global_load_dwordx4 v[34:37], v[4:5], off offset:3072 nt
	v_add_co_u32_e32 v4, vcc, s38, v2
	s_nop 1
	v_addc_co_u32_e32 v5, vcc, 0, v3, vcc
	global_load_dwordx4 v[30:33], v[4:5], off offset:1024 nt
	global_load_dwordx4 v[26:29], v[4:5], off offset:3072 nt
	v_add_co_u32_e32 v4, vcc, s39, v2
	s_nop 1
	v_addc_co_u32_e32 v5, vcc, 0, v3, vcc
	global_load_dwordx4 v[22:25], v[4:5], off offset:1024 nt
	global_load_dwordx4 v[18:21], v[4:5], off offset:3072 nt
	v_add_co_u32_e32 v4, vcc, s40, v2
	s_nop 1
	v_addc_co_u32_e32 v5, vcc, 0, v3, vcc
	v_add_co_u32_e32 v2, vcc, s41, v2
	global_load_dwordx4 v[14:17], v[4:5], off offset:1024 nt
	global_load_dwordx4 v[10:13], v[4:5], off offset:3072 nt
	v_addc_co_u32_e32 v3, vcc, 0, v3, vcc
	global_load_dwordx4 v[6:9], v[2:3], off offset:1024 nt
	s_nop 0
	global_load_dwordx4 v[2:5], v[2:3], off offset:3072 nt
	s_waitcnt vmcnt(32)
	v_lshlrev_b32_e32 v135, 16, v108
	v_and_b32_e32 v137, 0xffff0000, v108
	v_lshlrev_b32_e32 v136, 16, v109
	v_and_b32_e32 v134, 0xffff0000, v109
	v_and_b32_e32 v108, 31, v1
	v_cmp_eq_u32_e64 s[2:3], 0, v108
	v_lshlrev_b32_e32 v108, 5, v1
	v_and_b32_e32 v133, 0x400, v108
	s_waitcnt vmcnt(31)
	v_mul_f32_e32 v108, v139, v137
	v_fmac_f32_e32 v108, v138, v135
	v_fmac_f32_e32 v108, v140, v136
	v_fmac_f32_e32 v108, v141, v134
	s_lshl_b32 s19, s43, 7
	s_add_i32 s19, s19, 0
	v_add_f32_dpp v108, v108, v108 quad_perm:[1,0,3,2] row_mask:0xf bank_mask:0xf bound_ctrl:1
	v_add_u32_e32 v138, s19, v133
	s_nop 0
	v_add_f32_dpp v108, v108, v108 quad_perm:[2,3,0,1] row_mask:0xf bank_mask:0xf bound_ctrl:1
	s_nop 1
	v_add_f32_dpp v108, v108, v108 row_ror:4 row_mask:0xf bank_mask:0xf bound_ctrl:1
	s_nop 1
	v_add_f32_dpp v108, v108, v108 row_ror:8 row_mask:0xf bank_mask:0xf bound_ctrl:1
	v_mov_b32_e32 v109, v108
	s_nop 1
	v_permlane16_swap_b32_e32 v108, v109
	s_and_saveexec_b64 s[20:21], s[2:3]
	v_add_f32_e32 v108, v108, v109
	ds_write_b32 v138, v108
	s_or_b64 exec, exec, s[20:21]
	s_waitcnt vmcnt(30)
	v_mul_f32_e32 v103, v103, v137
	v_fmac_f32_e32 v103, v102, v135
	v_fmac_f32_e32 v103, v104, v136
	v_fmac_f32_e32 v103, v105, v134
	s_nop 1
	v_add_f32_dpp v102, v103, v103 quad_perm:[1,0,3,2] row_mask:0xf bank_mask:0xf bound_ctrl:1
	s_nop 1
	v_add_f32_dpp v102, v102, v102 quad_perm:[2,3,0,1] row_mask:0xf bank_mask:0xf bound_ctrl:1
	s_nop 1
	v_add_f32_dpp v102, v102, v102 row_ror:4 row_mask:0xf bank_mask:0xf bound_ctrl:1
	s_nop 1
	v_add_f32_dpp v102, v102, v102 row_ror:8 row_mask:0xf bank_mask:0xf bound_ctrl:1
	v_mov_b32_e32 v103, v102
	s_nop 1
	v_permlane16_swap_b32_e32 v102, v103
	s_and_saveexec_b64 s[20:21], s[2:3]
	v_add_f32_e32 v102, v102, v103
	ds_write_b32 v138, v102 offset:4
	s_or_b64 exec, exec, s[20:21]
	s_waitcnt vmcnt(29)
	v_mul_f32_e32 v99, v99, v137
	v_fmac_f32_e32 v99, v98, v135
	v_fmac_f32_e32 v99, v100, v136
	v_fmac_f32_e32 v99, v101, v134
	s_nop 1
	v_add_f32_dpp v98, v99, v99 quad_perm:[1,0,3,2] row_mask:0xf bank_mask:0xf bound_ctrl:1
	s_nop 1
	v_add_f32_dpp v98, v98, v98 quad_perm:[2,3,0,1] row_mask:0xf bank_mask:0xf bound_ctrl:1
	s_nop 1
	v_add_f32_dpp v98, v98, v98 row_ror:4 row_mask:0xf bank_mask:0xf bound_ctrl:1
	s_nop 1
	v_add_f32_dpp v98, v98, v98 row_ror:8 row_mask:0xf bank_mask:0xf bound_ctrl:1
	v_mov_b32_e32 v99, v98
	s_nop 1
	v_permlane16_swap_b32_e32 v98, v99
	s_and_saveexec_b64 s[20:21], s[2:3]
	v_add_f32_e32 v98, v98, v99
	ds_write_b32 v138, v98 offset:8
	s_or_b64 exec, exec, s[20:21]
	s_waitcnt vmcnt(28)
	v_mul_f32_e32 v95, v95, v137
	v_fmac_f32_e32 v95, v94, v135
	v_fmac_f32_e32 v95, v96, v136
	v_fmac_f32_e32 v95, v97, v134
	s_nop 1
	v_add_f32_dpp v94, v95, v95 quad_perm:[1,0,3,2] row_mask:0xf bank_mask:0xf bound_ctrl:1
	s_nop 1
	v_add_f32_dpp v94, v94, v94 quad_perm:[2,3,0,1] row_mask:0xf bank_mask:0xf bound_ctrl:1
	s_nop 1
	v_add_f32_dpp v94, v94, v94 row_ror:4 row_mask:0xf bank_mask:0xf bound_ctrl:1
	s_nop 1
	v_add_f32_dpp v94, v94, v94 row_ror:8 row_mask:0xf bank_mask:0xf bound_ctrl:1
	v_mov_b32_e32 v95, v94
	s_nop 1
	v_permlane16_swap_b32_e32 v94, v95
	s_and_saveexec_b64 s[20:21], s[2:3]
	v_add_f32_e32 v94, v94, v95
	ds_write_b32 v138, v94 offset:12
	s_or_b64 exec, exec, s[20:21]
	s_waitcnt vmcnt(27)
	v_mul_f32_e32 v91, v91, v137
	v_fmac_f32_e32 v91, v90, v135
	v_fmac_f32_e32 v91, v92, v136
	v_fmac_f32_e32 v91, v93, v134
	s_nop 1
	v_add_f32_dpp v90, v91, v91 quad_perm:[1,0,3,2] row_mask:0xf bank_mask:0xf bound_ctrl:1
	s_nop 1
	v_add_f32_dpp v90, v90, v90 quad_perm:[2,3,0,1] row_mask:0xf bank_mask:0xf bound_ctrl:1
	s_nop 1
	v_add_f32_dpp v90, v90, v90 row_ror:4 row_mask:0xf bank_mask:0xf bound_ctrl:1
	s_nop 1
	v_add_f32_dpp v90, v90, v90 row_ror:8 row_mask:0xf bank_mask:0xf bound_ctrl:1
	v_mov_b32_e32 v91, v90
	s_nop 1
	v_permlane16_swap_b32_e32 v90, v91
	s_and_saveexec_b64 s[20:21], s[2:3]
	v_add_f32_e32 v90, v90, v91
	ds_write_b32 v138, v90 offset:16
	s_or_b64 exec, exec, s[20:21]
	s_waitcnt vmcnt(26)
	v_mul_f32_e32 v87, v87, v137
	v_fmac_f32_e32 v87, v86, v135
	v_fmac_f32_e32 v87, v88, v136
	v_fmac_f32_e32 v87, v89, v134
	s_nop 1
	v_add_f32_dpp v86, v87, v87 quad_perm:[1,0,3,2] row_mask:0xf bank_mask:0xf bound_ctrl:1
	s_nop 1
	v_add_f32_dpp v86, v86, v86 quad_perm:[2,3,0,1] row_mask:0xf bank_mask:0xf bound_ctrl:1
	s_nop 1
	v_add_f32_dpp v86, v86, v86 row_ror:4 row_mask:0xf bank_mask:0xf bound_ctrl:1
	s_nop 1
	v_add_f32_dpp v86, v86, v86 row_ror:8 row_mask:0xf bank_mask:0xf bound_ctrl:1
	v_mov_b32_e32 v87, v86
	s_nop 1
	v_permlane16_swap_b32_e32 v86, v87
	s_and_saveexec_b64 s[20:21], s[2:3]
	v_add_f32_e32 v86, v86, v87
	ds_write_b32 v138, v86 offset:20
	s_or_b64 exec, exec, s[20:21]
	s_waitcnt vmcnt(25)
	v_mul_f32_e32 v83, v83, v137
	v_fmac_f32_e32 v83, v82, v135
	v_fmac_f32_e32 v83, v84, v136
	v_fmac_f32_e32 v83, v85, v134
	s_nop 1
	v_add_f32_dpp v82, v83, v83 quad_perm:[1,0,3,2] row_mask:0xf bank_mask:0xf bound_ctrl:1
	s_nop 1
	v_add_f32_dpp v82, v82, v82 quad_perm:[2,3,0,1] row_mask:0xf bank_mask:0xf bound_ctrl:1
	s_nop 1
	v_add_f32_dpp v82, v82, v82 row_ror:4 row_mask:0xf bank_mask:0xf bound_ctrl:1
	s_nop 1
	v_add_f32_dpp v82, v82, v82 row_ror:8 row_mask:0xf bank_mask:0xf bound_ctrl:1
	v_mov_b32_e32 v83, v82
	s_nop 1
	v_permlane16_swap_b32_e32 v82, v83
	s_and_saveexec_b64 s[20:21], s[2:3]
	v_add_f32_e32 v82, v82, v83
	ds_write_b32 v138, v82 offset:24
	s_or_b64 exec, exec, s[20:21]
	s_waitcnt vmcnt(24)
	v_mul_f32_e32 v79, v79, v137
	v_fmac_f32_e32 v79, v78, v135
	v_fmac_f32_e32 v79, v80, v136
	v_fmac_f32_e32 v79, v81, v134
	s_nop 1
	v_add_f32_dpp v78, v79, v79 quad_perm:[1,0,3,2] row_mask:0xf bank_mask:0xf bound_ctrl:1
	s_nop 1
	v_add_f32_dpp v78, v78, v78 quad_perm:[2,3,0,1] row_mask:0xf bank_mask:0xf bound_ctrl:1
	s_nop 1
	v_add_f32_dpp v78, v78, v78 row_ror:4 row_mask:0xf bank_mask:0xf bound_ctrl:1
	s_nop 1
	v_add_f32_dpp v78, v78, v78 row_ror:8 row_mask:0xf bank_mask:0xf bound_ctrl:1
	v_mov_b32_e32 v79, v78
	s_nop 1
	v_permlane16_swap_b32_e32 v78, v79
	s_and_saveexec_b64 s[20:21], s[2:3]
	v_add_f32_e32 v78, v78, v79
	ds_write_b32 v138, v78 offset:28
	s_or_b64 exec, exec, s[20:21]
	s_waitcnt vmcnt(23)
	v_mul_f32_e32 v75, v75, v137
	v_fmac_f32_e32 v75, v74, v135
	v_fmac_f32_e32 v75, v76, v136
	v_fmac_f32_e32 v75, v77, v134
	s_nop 1
	v_add_f32_dpp v74, v75, v75 quad_perm:[1,0,3,2] row_mask:0xf bank_mask:0xf bound_ctrl:1
	s_nop 1
	v_add_f32_dpp v74, v74, v74 quad_perm:[2,3,0,1] row_mask:0xf bank_mask:0xf bound_ctrl:1
	s_nop 1
	v_add_f32_dpp v74, v74, v74 row_ror:4 row_mask:0xf bank_mask:0xf bound_ctrl:1
	s_nop 1
	v_add_f32_dpp v74, v74, v74 row_ror:8 row_mask:0xf bank_mask:0xf bound_ctrl:1
	v_mov_b32_e32 v75, v74
	s_nop 1
	v_permlane16_swap_b32_e32 v74, v75
	s_and_saveexec_b64 s[20:21], s[2:3]
	v_add_f32_e32 v74, v74, v75
	ds_write_b32 v138, v74 offset:32
	s_or_b64 exec, exec, s[20:21]
	s_waitcnt vmcnt(22)
	v_mul_f32_e32 v71, v71, v137
	v_fmac_f32_e32 v71, v70, v135
	v_fmac_f32_e32 v71, v72, v136
	v_fmac_f32_e32 v71, v73, v134
	s_nop 1
	v_add_f32_dpp v70, v71, v71 quad_perm:[1,0,3,2] row_mask:0xf bank_mask:0xf bound_ctrl:1
	s_nop 1
	v_add_f32_dpp v70, v70, v70 quad_perm:[2,3,0,1] row_mask:0xf bank_mask:0xf bound_ctrl:1
	s_nop 1
	v_add_f32_dpp v70, v70, v70 row_ror:4 row_mask:0xf bank_mask:0xf bound_ctrl:1
	s_nop 1
	v_add_f32_dpp v70, v70, v70 row_ror:8 row_mask:0xf bank_mask:0xf bound_ctrl:1
	v_mov_b32_e32 v71, v70
	s_nop 1
	v_permlane16_swap_b32_e32 v70, v71
	s_and_saveexec_b64 s[20:21], s[2:3]
	v_add_f32_e32 v70, v70, v71
	ds_write_b32 v138, v70 offset:36
	s_or_b64 exec, exec, s[20:21]
	s_waitcnt vmcnt(21)
	v_mul_f32_e32 v67, v67, v137
	v_fmac_f32_e32 v67, v66, v135
	v_fmac_f32_e32 v67, v68, v136
	v_fmac_f32_e32 v67, v69, v134
	s_nop 1
	v_add_f32_dpp v66, v67, v67 quad_perm:[1,0,3,2] row_mask:0xf bank_mask:0xf bound_ctrl:1
	s_nop 1
	v_add_f32_dpp v66, v66, v66 quad_perm:[2,3,0,1] row_mask:0xf bank_mask:0xf bound_ctrl:1
	s_nop 1
	v_add_f32_dpp v66, v66, v66 row_ror:4 row_mask:0xf bank_mask:0xf bound_ctrl:1
	s_nop 1
	v_add_f32_dpp v66, v66, v66 row_ror:8 row_mask:0xf bank_mask:0xf bound_ctrl:1
	v_mov_b32_e32 v67, v66
	s_nop 1
	v_permlane16_swap_b32_e32 v66, v67
	s_and_saveexec_b64 s[20:21], s[2:3]
	v_add_f32_e32 v66, v66, v67
	ds_write_b32 v138, v66 offset:40
	s_or_b64 exec, exec, s[20:21]
	s_waitcnt vmcnt(20)
	v_mul_f32_e32 v63, v63, v137
	v_fmac_f32_e32 v63, v62, v135
	v_fmac_f32_e32 v63, v64, v136
	v_fmac_f32_e32 v63, v65, v134
	s_nop 1
	v_add_f32_dpp v62, v63, v63 quad_perm:[1,0,3,2] row_mask:0xf bank_mask:0xf bound_ctrl:1
	s_nop 1
	v_add_f32_dpp v62, v62, v62 quad_perm:[2,3,0,1] row_mask:0xf bank_mask:0xf bound_ctrl:1
	s_nop 1
	v_add_f32_dpp v62, v62, v62 row_ror:4 row_mask:0xf bank_mask:0xf bound_ctrl:1
	s_nop 1
	v_add_f32_dpp v62, v62, v62 row_ror:8 row_mask:0xf bank_mask:0xf bound_ctrl:1
	v_mov_b32_e32 v63, v62
	s_nop 1
	v_permlane16_swap_b32_e32 v62, v63
	s_and_saveexec_b64 s[20:21], s[2:3]
	v_add_f32_e32 v62, v62, v63
	ds_write_b32 v138, v62 offset:44
	s_or_b64 exec, exec, s[20:21]
	s_waitcnt vmcnt(19)
	v_mul_f32_e32 v59, v59, v137
	v_fmac_f32_e32 v59, v58, v135
	v_fmac_f32_e32 v59, v60, v136
	v_fmac_f32_e32 v59, v61, v134
	s_nop 1
	v_add_f32_dpp v58, v59, v59 quad_perm:[1,0,3,2] row_mask:0xf bank_mask:0xf bound_ctrl:1
	s_nop 1
	v_add_f32_dpp v58, v58, v58 quad_perm:[2,3,0,1] row_mask:0xf bank_mask:0xf bound_ctrl:1
	s_nop 1
	v_add_f32_dpp v58, v58, v58 row_ror:4 row_mask:0xf bank_mask:0xf bound_ctrl:1
	s_nop 1
	v_add_f32_dpp v58, v58, v58 row_ror:8 row_mask:0xf bank_mask:0xf bound_ctrl:1
	v_mov_b32_e32 v59, v58
	s_nop 1
	v_permlane16_swap_b32_e32 v58, v59
	s_and_saveexec_b64 s[20:21], s[2:3]
	v_add_f32_e32 v58, v58, v59
	ds_write_b32 v138, v58 offset:48
	s_or_b64 exec, exec, s[20:21]
	s_waitcnt vmcnt(18)
	v_mul_f32_e32 v55, v55, v137
	v_fmac_f32_e32 v55, v54, v135
	v_fmac_f32_e32 v55, v56, v136
	v_fmac_f32_e32 v55, v57, v134
	s_nop 1
	v_add_f32_dpp v54, v55, v55 quad_perm:[1,0,3,2] row_mask:0xf bank_mask:0xf bound_ctrl:1
	s_nop 1
	v_add_f32_dpp v54, v54, v54 quad_perm:[2,3,0,1] row_mask:0xf bank_mask:0xf bound_ctrl:1
	s_nop 1
	v_add_f32_dpp v54, v54, v54 row_ror:4 row_mask:0xf bank_mask:0xf bound_ctrl:1
	s_nop 1
	v_add_f32_dpp v54, v54, v54 row_ror:8 row_mask:0xf bank_mask:0xf bound_ctrl:1
	v_mov_b32_e32 v55, v54
	s_nop 1
	v_permlane16_swap_b32_e32 v54, v55
	s_and_saveexec_b64 s[20:21], s[2:3]
	v_add_f32_e32 v54, v54, v55
	ds_write_b32 v138, v54 offset:52
	s_or_b64 exec, exec, s[20:21]
	s_waitcnt vmcnt(17)
	v_mul_f32_e32 v51, v51, v137
	v_fmac_f32_e32 v51, v50, v135
	v_fmac_f32_e32 v51, v52, v136
	v_fmac_f32_e32 v51, v53, v134
	s_nop 1
	v_add_f32_dpp v50, v51, v51 quad_perm:[1,0,3,2] row_mask:0xf bank_mask:0xf bound_ctrl:1
	s_nop 1
	v_add_f32_dpp v50, v50, v50 quad_perm:[2,3,0,1] row_mask:0xf bank_mask:0xf bound_ctrl:1
	s_nop 1
	v_add_f32_dpp v50, v50, v50 row_ror:4 row_mask:0xf bank_mask:0xf bound_ctrl:1
	s_nop 1
	v_add_f32_dpp v50, v50, v50 row_ror:8 row_mask:0xf bank_mask:0xf bound_ctrl:1
	v_mov_b32_e32 v51, v50
	s_nop 1
	v_permlane16_swap_b32_e32 v50, v51
	s_and_saveexec_b64 s[20:21], s[2:3]
	v_add_f32_e32 v50, v50, v51
	ds_write_b32 v138, v50 offset:56
	s_or_b64 exec, exec, s[20:21]
	s_waitcnt vmcnt(16)
	v_mul_f32_e32 v47, v47, v137
	v_fmac_f32_e32 v47, v46, v135
	v_fmac_f32_e32 v47, v48, v136
	v_fmac_f32_e32 v47, v49, v134
	s_nop 1
	v_add_f32_dpp v46, v47, v47 quad_perm:[1,0,3,2] row_mask:0xf bank_mask:0xf bound_ctrl:1
	s_nop 1
	v_add_f32_dpp v46, v46, v46 quad_perm:[2,3,0,1] row_mask:0xf bank_mask:0xf bound_ctrl:1
	s_nop 1
	v_add_f32_dpp v46, v46, v46 row_ror:4 row_mask:0xf bank_mask:0xf bound_ctrl:1
	s_nop 1
	v_add_f32_dpp v46, v46, v46 row_ror:8 row_mask:0xf bank_mask:0xf bound_ctrl:1
	v_mov_b32_e32 v47, v46
	s_nop 1
	v_permlane16_swap_b32_e32 v46, v47
	s_and_saveexec_b64 s[20:21], s[2:3]
	v_add_f32_e32 v46, v46, v47
	ds_write_b32 v138, v46 offset:60
	s_or_b64 exec, exec, s[20:21]
	v_readlane_b32 s44, v245, 9
	v_readlane_b32 s45, v245, 10
	s_add_u32 s20, s44, s6
	s_addc_u32 s21, s45, s7
	v_lshl_add_u64 v[130:131], s[20:21], 0, v[106:107]
	v_readlane_b32 s46, v245, 11
	v_readlane_b32 s47, v245, 12
	v_readlane_b32 s48, v245, 13
	v_readlane_b32 s49, v245, 14
	v_readlane_b32 s50, v245, 15
	v_readlane_b32 s51, v245, 16
	v_readlane_b32 s52, v245, 17
	v_readlane_b32 s53, v245, 18
	v_readlane_b32 s54, v245, 19
	v_readlane_b32 s55, v245, 20
	v_readlane_b32 s56, v245, 21
	v_readlane_b32 s57, v245, 22
	v_readlane_b32 s58, v245, 23
	v_readlane_b32 s59, v245, 24
	v_add_co_u32_e32 v46, vcc, 0x1000, v130
	global_load_dwordx4 v[106:109], v[130:131], off offset:1024 nt
	global_load_dwordx4 v[94:97], v[130:131], off offset:3072 nt
	v_addc_co_u32_e32 v47, vcc, 0, v131, vcc
	global_load_dwordx4 v[102:105], v[46:47], off offset:1024 nt
	global_load_dwordx4 v[78:81], v[46:47], off offset:3072 nt
	v_add_co_u32_e32 v46, vcc, 0x2000, v130
	s_nop 1
	v_addc_co_u32_e32 v47, vcc, 0, v131, vcc
	global_load_dwordx4 v[98:101], v[46:47], off offset:1024 nt
	global_load_dwordx4 v[82:85], v[46:47], off offset:3072 nt
	v_add_co_u32_e32 v46, vcc, 0x3000, v130
	s_nop 1
	v_addc_co_u32_e32 v47, vcc, 0, v131, vcc
	global_load_dwordx4 v[90:93], v[46:47], off offset:1024 nt
	global_load_dwordx4 v[62:65], v[46:47], off offset:3072 nt
	v_add_co_u32_e32 v46, vcc, 0x4000, v130
	s_nop 1
	v_addc_co_u32_e32 v47, vcc, 0, v131, vcc
	global_load_dwordx4 v[86:89], v[46:47], off offset:1024 nt
	global_load_dwordx4 v[66:69], v[46:47], off offset:3072 nt
	v_add_co_u32_e32 v46, vcc, 0x5000, v130
	s_nop 1
	v_addc_co_u32_e32 v47, vcc, 0, v131, vcc
	global_load_dwordx4 v[74:77], v[46:47], off offset:1024 nt
	global_load_dwordx4 v[50:53], v[46:47], off offset:3072 nt
	v_add_co_u32_e32 v46, vcc, 0x6000, v130
	s_nop 1
	v_addc_co_u32_e32 v47, vcc, 0, v131, vcc
	global_load_dwordx4 v[70:73], v[46:47], off offset:1024 nt
	global_load_dwordx4 v[54:57], v[46:47], off offset:3072 nt
	v_add_co_u32_e32 v46, vcc, 0x7000, v130
	s_nop 1
	v_addc_co_u32_e32 v47, vcc, 0, v131, vcc
	global_load_dwordx4 v[58:61], v[46:47], off offset:1024 nt
	s_nop 0
	global_load_dwordx4 v[46:49], v[46:47], off offset:3072 nt
	s_waitcnt vmcnt(31)
	v_mul_f32_e32 v127, v127, v137
	v_fmac_f32_e32 v127, v126, v135
	v_fmac_f32_e32 v127, v128, v136
	v_fmac_f32_e32 v127, v129, v134
	s_nop 1
	v_add_f32_dpp v126, v127, v127 quad_perm:[1,0,3,2] row_mask:0xf bank_mask:0xf bound_ctrl:1
	s_nop 1
	v_add_f32_dpp v126, v126, v126 quad_perm:[2,3,0,1] row_mask:0xf bank_mask:0xf bound_ctrl:1
	s_nop 1
	v_add_f32_dpp v126, v126, v126 row_ror:4 row_mask:0xf bank_mask:0xf bound_ctrl:1
	s_nop 1
	v_add_f32_dpp v126, v126, v126 row_ror:8 row_mask:0xf bank_mask:0xf bound_ctrl:1
	v_mov_b32_e32 v127, v126
	s_nop 1
	v_permlane16_swap_b32_e32 v126, v127
	s_and_saveexec_b64 s[20:21], s[2:3]
	v_add_f32_e32 v126, v126, v127
	ds_write_b32 v138, v126 offset:64
	s_or_b64 exec, exec, s[20:21]
	s_waitcnt vmcnt(30)
	v_mul_f32_e32 v123, v123, v137
	v_fmac_f32_e32 v123, v122, v135
	v_fmac_f32_e32 v123, v124, v136
	v_fmac_f32_e32 v123, v125, v134
	s_nop 1
	v_add_f32_dpp v122, v123, v123 quad_perm:[1,0,3,2] row_mask:0xf bank_mask:0xf bound_ctrl:1
	s_nop 1
	v_add_f32_dpp v122, v122, v122 quad_perm:[2,3,0,1] row_mask:0xf bank_mask:0xf bound_ctrl:1
	s_nop 1
	v_add_f32_dpp v122, v122, v122 row_ror:4 row_mask:0xf bank_mask:0xf bound_ctrl:1
	s_nop 1
	v_add_f32_dpp v122, v122, v122 row_ror:8 row_mask:0xf bank_mask:0xf bound_ctrl:1
	v_mov_b32_e32 v123, v122
	s_nop 1
	v_permlane16_swap_b32_e32 v122, v123
	s_and_saveexec_b64 s[20:21], s[2:3]
	v_add_f32_e32 v122, v122, v123
	ds_write_b32 v138, v122 offset:68
	s_or_b64 exec, exec, s[20:21]
	s_waitcnt vmcnt(29)
	v_mul_f32_e32 v119, v119, v137
	v_fmac_f32_e32 v119, v118, v135
	v_fmac_f32_e32 v119, v120, v136
	v_fmac_f32_e32 v119, v121, v134
	s_nop 1
	v_add_f32_dpp v118, v119, v119 quad_perm:[1,0,3,2] row_mask:0xf bank_mask:0xf bound_ctrl:1
	s_nop 1
	v_add_f32_dpp v118, v118, v118 quad_perm:[2,3,0,1] row_mask:0xf bank_mask:0xf bound_ctrl:1
	s_nop 1
	v_add_f32_dpp v118, v118, v118 row_ror:4 row_mask:0xf bank_mask:0xf bound_ctrl:1
	s_nop 1
	v_add_f32_dpp v118, v118, v118 row_ror:8 row_mask:0xf bank_mask:0xf bound_ctrl:1
	v_mov_b32_e32 v119, v118
	s_nop 1
	v_permlane16_swap_b32_e32 v118, v119
	s_and_saveexec_b64 s[20:21], s[2:3]
	v_add_f32_e32 v118, v118, v119
	ds_write_b32 v138, v118 offset:72
	s_or_b64 exec, exec, s[20:21]
	s_waitcnt vmcnt(28)
	v_mul_f32_e32 v115, v115, v137
	v_fmac_f32_e32 v115, v114, v135
	v_fmac_f32_e32 v115, v116, v136
	v_fmac_f32_e32 v115, v117, v134
	s_nop 1
	v_add_f32_dpp v114, v115, v115 quad_perm:[1,0,3,2] row_mask:0xf bank_mask:0xf bound_ctrl:1
	s_nop 1
	v_add_f32_dpp v114, v114, v114 quad_perm:[2,3,0,1] row_mask:0xf bank_mask:0xf bound_ctrl:1
	s_nop 1
	v_add_f32_dpp v114, v114, v114 row_ror:4 row_mask:0xf bank_mask:0xf bound_ctrl:1
	s_nop 1
	v_add_f32_dpp v114, v114, v114 row_ror:8 row_mask:0xf bank_mask:0xf bound_ctrl:1
	v_mov_b32_e32 v115, v114
	s_nop 1
	v_permlane16_swap_b32_e32 v114, v115
	s_and_saveexec_b64 s[20:21], s[2:3]
	v_add_f32_e32 v114, v114, v115
	ds_write_b32 v138, v114 offset:76
	s_or_b64 exec, exec, s[20:21]
	s_waitcnt vmcnt(27)
	v_mul_f32_e32 v111, v111, v137
	v_fmac_f32_e32 v111, v110, v135
	v_fmac_f32_e32 v111, v112, v136
	v_fmac_f32_e32 v111, v113, v134
	s_nop 1
	v_add_f32_dpp v110, v111, v111 quad_perm:[1,0,3,2] row_mask:0xf bank_mask:0xf bound_ctrl:1
	s_nop 1
	v_add_f32_dpp v110, v110, v110 quad_perm:[2,3,0,1] row_mask:0xf bank_mask:0xf bound_ctrl:1
	s_nop 1
	v_add_f32_dpp v110, v110, v110 row_ror:4 row_mask:0xf bank_mask:0xf bound_ctrl:1
	s_nop 1
	v_add_f32_dpp v110, v110, v110 row_ror:8 row_mask:0xf bank_mask:0xf bound_ctrl:1
	v_mov_b32_e32 v111, v110
	s_nop 1
	v_permlane16_swap_b32_e32 v110, v111
	s_and_saveexec_b64 s[20:21], s[2:3]
	v_add_f32_e32 v110, v110, v111
	ds_write_b32 v138, v110 offset:80
	s_or_b64 exec, exec, s[20:21]
	s_waitcnt vmcnt(26)
	v_mul_f32_e32 v43, v43, v137
	v_fmac_f32_e32 v43, v42, v135
	v_fmac_f32_e32 v43, v44, v136
	v_fmac_f32_e32 v43, v45, v134
	s_nop 1
	v_add_f32_dpp v42, v43, v43 quad_perm:[1,0,3,2] row_mask:0xf bank_mask:0xf bound_ctrl:1
	s_nop 1
	v_add_f32_dpp v42, v42, v42 quad_perm:[2,3,0,1] row_mask:0xf bank_mask:0xf bound_ctrl:1
	s_nop 1
	v_add_f32_dpp v42, v42, v42 row_ror:4 row_mask:0xf bank_mask:0xf bound_ctrl:1
	s_nop 1
	v_add_f32_dpp v42, v42, v42 row_ror:8 row_mask:0xf bank_mask:0xf bound_ctrl:1
	v_mov_b32_e32 v43, v42
	s_nop 1
	v_permlane16_swap_b32_e32 v42, v43
	s_and_saveexec_b64 s[20:21], s[2:3]
	v_add_f32_e32 v42, v42, v43
	ds_write_b32 v138, v42 offset:84
	s_or_b64 exec, exec, s[20:21]
	s_waitcnt vmcnt(25)
	v_mul_f32_e32 v39, v39, v137
	v_fmac_f32_e32 v39, v38, v135
	v_fmac_f32_e32 v39, v40, v136
	v_fmac_f32_e32 v39, v41, v134
	s_nop 1
	v_add_f32_dpp v38, v39, v39 quad_perm:[1,0,3,2] row_mask:0xf bank_mask:0xf bound_ctrl:1
	s_nop 1
	v_add_f32_dpp v38, v38, v38 quad_perm:[2,3,0,1] row_mask:0xf bank_mask:0xf bound_ctrl:1
	s_nop 1
	v_add_f32_dpp v38, v38, v38 row_ror:4 row_mask:0xf bank_mask:0xf bound_ctrl:1
	s_nop 1
	v_add_f32_dpp v38, v38, v38 row_ror:8 row_mask:0xf bank_mask:0xf bound_ctrl:1
	v_mov_b32_e32 v39, v38
	s_nop 1
	v_permlane16_swap_b32_e32 v38, v39
	s_and_saveexec_b64 s[20:21], s[2:3]
	v_add_f32_e32 v38, v38, v39
	ds_write_b32 v138, v38 offset:88
	s_or_b64 exec, exec, s[20:21]
	s_waitcnt vmcnt(24)
	v_mul_f32_e32 v35, v35, v137
	v_fmac_f32_e32 v35, v34, v135
	v_fmac_f32_e32 v35, v36, v136
	v_fmac_f32_e32 v35, v37, v134
	s_nop 1
	v_add_f32_dpp v34, v35, v35 quad_perm:[1,0,3,2] row_mask:0xf bank_mask:0xf bound_ctrl:1
	s_nop 1
	v_add_f32_dpp v34, v34, v34 quad_perm:[2,3,0,1] row_mask:0xf bank_mask:0xf bound_ctrl:1
	s_nop 1
	v_add_f32_dpp v34, v34, v34 row_ror:4 row_mask:0xf bank_mask:0xf bound_ctrl:1
	s_nop 1
	v_add_f32_dpp v34, v34, v34 row_ror:8 row_mask:0xf bank_mask:0xf bound_ctrl:1
	v_mov_b32_e32 v35, v34
	s_nop 1
	v_permlane16_swap_b32_e32 v34, v35
	s_and_saveexec_b64 s[20:21], s[2:3]
	v_add_f32_e32 v34, v34, v35
	ds_write_b32 v138, v34 offset:92
	s_or_b64 exec, exec, s[20:21]
	s_waitcnt vmcnt(23)
	v_mul_f32_e32 v31, v31, v137
	v_fmac_f32_e32 v31, v30, v135
	v_fmac_f32_e32 v31, v32, v136
	v_fmac_f32_e32 v31, v33, v134
	s_nop 1
	v_add_f32_dpp v30, v31, v31 quad_perm:[1,0,3,2] row_mask:0xf bank_mask:0xf bound_ctrl:1
	s_nop 1
	v_add_f32_dpp v30, v30, v30 quad_perm:[2,3,0,1] row_mask:0xf bank_mask:0xf bound_ctrl:1
	s_nop 1
	v_add_f32_dpp v30, v30, v30 row_ror:4 row_mask:0xf bank_mask:0xf bound_ctrl:1
	s_nop 1
	v_add_f32_dpp v30, v30, v30 row_ror:8 row_mask:0xf bank_mask:0xf bound_ctrl:1
	v_mov_b32_e32 v31, v30
	s_nop 1
	v_permlane16_swap_b32_e32 v30, v31
	s_and_saveexec_b64 s[20:21], s[2:3]
	v_add_f32_e32 v30, v30, v31
	ds_write_b32 v138, v30 offset:96
	s_or_b64 exec, exec, s[20:21]
	s_waitcnt vmcnt(22)
	v_mul_f32_e32 v27, v27, v137
	v_fmac_f32_e32 v27, v26, v135
	v_fmac_f32_e32 v27, v28, v136
	v_fmac_f32_e32 v27, v29, v134
	s_nop 1
	v_add_f32_dpp v26, v27, v27 quad_perm:[1,0,3,2] row_mask:0xf bank_mask:0xf bound_ctrl:1
	s_nop 1
	v_add_f32_dpp v26, v26, v26 quad_perm:[2,3,0,1] row_mask:0xf bank_mask:0xf bound_ctrl:1
	s_nop 1
	v_add_f32_dpp v26, v26, v26 row_ror:4 row_mask:0xf bank_mask:0xf bound_ctrl:1
	s_nop 1
	v_add_f32_dpp v26, v26, v26 row_ror:8 row_mask:0xf bank_mask:0xf bound_ctrl:1
	v_mov_b32_e32 v27, v26
	s_nop 1
	v_permlane16_swap_b32_e32 v26, v27
	s_and_saveexec_b64 s[20:21], s[2:3]
	v_add_f32_e32 v26, v26, v27
	ds_write_b32 v138, v26 offset:100
	s_or_b64 exec, exec, s[20:21]
	s_waitcnt vmcnt(21)
	v_mul_f32_e32 v23, v23, v137
	v_fmac_f32_e32 v23, v22, v135
	v_fmac_f32_e32 v23, v24, v136
	v_fmac_f32_e32 v23, v25, v134
	s_nop 1
	v_add_f32_dpp v22, v23, v23 quad_perm:[1,0,3,2] row_mask:0xf bank_mask:0xf bound_ctrl:1
	s_nop 1
	v_add_f32_dpp v22, v22, v22 quad_perm:[2,3,0,1] row_mask:0xf bank_mask:0xf bound_ctrl:1
	s_nop 1
	v_add_f32_dpp v22, v22, v22 row_ror:4 row_mask:0xf bank_mask:0xf bound_ctrl:1
	s_nop 1
	v_add_f32_dpp v22, v22, v22 row_ror:8 row_mask:0xf bank_mask:0xf bound_ctrl:1
	v_mov_b32_e32 v23, v22
	s_nop 1
	v_permlane16_swap_b32_e32 v22, v23
	s_and_saveexec_b64 s[20:21], s[2:3]
	v_add_f32_e32 v22, v22, v23
	ds_write_b32 v138, v22 offset:104
	s_or_b64 exec, exec, s[20:21]
	s_waitcnt vmcnt(20)
	v_mul_f32_e32 v19, v19, v137
	v_fmac_f32_e32 v19, v18, v135
	v_fmac_f32_e32 v19, v20, v136
	v_fmac_f32_e32 v19, v21, v134
	s_nop 1
	v_add_f32_dpp v18, v19, v19 quad_perm:[1,0,3,2] row_mask:0xf bank_mask:0xf bound_ctrl:1
	s_nop 1
	v_add_f32_dpp v18, v18, v18 quad_perm:[2,3,0,1] row_mask:0xf bank_mask:0xf bound_ctrl:1
	s_nop 1
	v_add_f32_dpp v18, v18, v18 row_ror:4 row_mask:0xf bank_mask:0xf bound_ctrl:1
	s_nop 1
	v_add_f32_dpp v18, v18, v18 row_ror:8 row_mask:0xf bank_mask:0xf bound_ctrl:1
	v_mov_b32_e32 v19, v18
	s_nop 1
	v_permlane16_swap_b32_e32 v18, v19
	s_and_saveexec_b64 s[20:21], s[2:3]
	v_add_f32_e32 v18, v18, v19
	ds_write_b32 v138, v18 offset:108
	s_or_b64 exec, exec, s[20:21]
	s_waitcnt vmcnt(19)
	v_mul_f32_e32 v15, v15, v137
	v_fmac_f32_e32 v15, v14, v135
	v_fmac_f32_e32 v15, v16, v136
	v_fmac_f32_e32 v15, v17, v134
	s_nop 1
	v_add_f32_dpp v14, v15, v15 quad_perm:[1,0,3,2] row_mask:0xf bank_mask:0xf bound_ctrl:1
	s_nop 1
	v_add_f32_dpp v14, v14, v14 quad_perm:[2,3,0,1] row_mask:0xf bank_mask:0xf bound_ctrl:1
	s_nop 1
	v_add_f32_dpp v14, v14, v14 row_ror:4 row_mask:0xf bank_mask:0xf bound_ctrl:1
	s_nop 1
	v_add_f32_dpp v14, v14, v14 row_ror:8 row_mask:0xf bank_mask:0xf bound_ctrl:1
	v_mov_b32_e32 v15, v14
	s_nop 1
	v_permlane16_swap_b32_e32 v14, v15
	s_and_saveexec_b64 s[20:21], s[2:3]
	v_add_f32_e32 v14, v14, v15
	ds_write_b32 v138, v14 offset:112
	s_or_b64 exec, exec, s[20:21]
	s_waitcnt vmcnt(18)
	v_mul_f32_e32 v11, v11, v137
	v_fmac_f32_e32 v11, v10, v135
	v_fmac_f32_e32 v11, v12, v136
	v_fmac_f32_e32 v11, v13, v134
	s_nop 1
	v_add_f32_dpp v10, v11, v11 quad_perm:[1,0,3,2] row_mask:0xf bank_mask:0xf bound_ctrl:1
	s_nop 1
	v_add_f32_dpp v10, v10, v10 quad_perm:[2,3,0,1] row_mask:0xf bank_mask:0xf bound_ctrl:1
	s_nop 1
	v_add_f32_dpp v10, v10, v10 row_ror:4 row_mask:0xf bank_mask:0xf bound_ctrl:1
	s_nop 1
	v_add_f32_dpp v10, v10, v10 row_ror:8 row_mask:0xf bank_mask:0xf bound_ctrl:1
	v_mov_b32_e32 v11, v10
	s_nop 1
	v_permlane16_swap_b32_e32 v10, v11
	s_and_saveexec_b64 s[20:21], s[2:3]
	v_add_f32_e32 v10, v10, v11
	ds_write_b32 v138, v10 offset:116
	s_or_b64 exec, exec, s[20:21]
	s_waitcnt vmcnt(17)
	v_mul_f32_e32 v7, v7, v137
	v_fmac_f32_e32 v7, v6, v135
	v_fmac_f32_e32 v7, v8, v136
	v_fmac_f32_e32 v7, v9, v134
	s_nop 1
	v_add_f32_dpp v6, v7, v7 quad_perm:[1,0,3,2] row_mask:0xf bank_mask:0xf bound_ctrl:1
	s_nop 1
	v_add_f32_dpp v6, v6, v6 quad_perm:[2,3,0,1] row_mask:0xf bank_mask:0xf bound_ctrl:1
	s_nop 1
	v_add_f32_dpp v6, v6, v6 row_ror:4 row_mask:0xf bank_mask:0xf bound_ctrl:1
	s_nop 1
	v_add_f32_dpp v6, v6, v6 row_ror:8 row_mask:0xf bank_mask:0xf bound_ctrl:1
	v_mov_b32_e32 v7, v6
	s_nop 1
	v_permlane16_swap_b32_e32 v6, v7
	s_and_saveexec_b64 s[20:21], s[2:3]
	v_add_f32_e32 v6, v6, v7
	ds_write_b32 v138, v6 offset:120
	s_or_b64 exec, exec, s[20:21]
	s_waitcnt vmcnt(16)
	v_mul_f32_e32 v3, v3, v137
	v_fmac_f32_e32 v3, v2, v135
	v_fmac_f32_e32 v3, v4, v136
	v_fmac_f32_e32 v3, v5, v134
	s_nop 1
	v_add_f32_dpp v2, v3, v3 quad_perm:[1,0,3,2] row_mask:0xf bank_mask:0xf bound_ctrl:1
	s_nop 1
	v_add_f32_dpp v2, v2, v2 quad_perm:[2,3,0,1] row_mask:0xf bank_mask:0xf bound_ctrl:1
	s_nop 1
	v_add_f32_dpp v2, v2, v2 row_ror:4 row_mask:0xf bank_mask:0xf bound_ctrl:1
	s_nop 1
	v_add_f32_dpp v2, v2, v2 row_ror:8 row_mask:0xf bank_mask:0xf bound_ctrl:1
	v_mov_b32_e32 v3, v2
	s_nop 1
	v_permlane16_swap_b32_e32 v2, v3
	s_and_saveexec_b64 s[20:21], s[2:3]
	v_add_f32_e32 v2, v2, v3
	ds_write_b32 v138, v2 offset:124
	s_or_b64 exec, exec, s[20:21]
	v_lshlrev_b32_e32 v134, 2, v132
	v_add_co_u32_e32 v2, vcc, 0x8000, v130
	s_nop 1
	v_addc_co_u32_e32 v3, vcc, 0, v131, vcc
	global_load_dwordx4 v[42:45], v[2:3], off offset:1024 nt
	global_load_dwordx4 v[38:41], v[2:3], off offset:3072 nt
	v_add_co_u32_e32 v2, vcc, 0x9000, v130
	s_nop 1
	v_addc_co_u32_e32 v3, vcc, 0, v131, vcc
	global_load_dwordx4 v[118:121], v[2:3], off offset:1024 nt
	global_load_dwordx4 v[110:113], v[2:3], off offset:3072 nt
	v_add_co_u32_e32 v2, vcc, 0xa000, v130
	s_nop 1
	v_addc_co_u32_e32 v3, vcc, 0, v131, vcc
	global_load_dwordx4 v[126:129], v[2:3], off offset:1024 nt
	global_load_dwordx4 v[114:117], v[2:3], off offset:3072 nt
	v_add_co_u32_e32 v2, vcc, 0xb000, v130
	s_nop 1
	v_addc_co_u32_e32 v3, vcc, 0, v131, vcc
	global_load_dwordx4 v[122:125], v[2:3], off offset:1024 nt
	global_load_dwordx4 v[34:37], v[2:3], off offset:3072 nt
	v_add_co_u32_e32 v2, vcc, 0xc000, v130
	s_nop 1
	v_addc_co_u32_e32 v3, vcc, 0, v131, vcc
	v_add_co_u32_e32 v6, vcc, 0xd000, v130
	global_load_dwordx4 v[10:13], v[2:3], off offset:1024 nt
	s_nop 0
	global_load_dwordx4 v[2:5], v[2:3], off offset:3072 nt
	v_addc_co_u32_e32 v7, vcc, 0, v131, vcc
	global_load_dwordx4 v[22:25], v[6:7], off offset:1024 nt
	global_load_dwordx4 v[14:17], v[6:7], off offset:3072 nt
	v_add_co_u32_e32 v6, vcc, 0xe000, v130
	s_nop 1
	v_addc_co_u32_e32 v7, vcc, 0, v131, vcc
	global_load_dwordx4 v[30:33], v[6:7], off offset:1024 nt
	global_load_dwordx4 v[18:21], v[6:7], off offset:3072 nt
	v_add_co_u32_e32 v6, vcc, 0xf000, v130
	s_nop 1
	v_addc_co_u32_e32 v7, vcc, 0, v131, vcc
	global_load_dwordx4 v[26:29], v[6:7], off offset:1024 nt
	s_nop 0
	global_load_dwordx4 v[6:9], v[6:7], off offset:3072 nt
	s_waitcnt lgkmcnt(0)
	s_barrier
	s_lshl_b32 s19, s43, 10
	s_cmp_gt_i32 s43, 1
	s_cbranch_scc1 .LBB0_880
	s_add_i32 s20, s19, 0
	v_lshl_add_u32 v135, v134, 2, s20
	ds_read_b128 v[136:139], v135
	v_cmp_eq_u32_e32 vcc, 0, v132
	s_waitcnt lgkmcnt(0)
	v_max_f32_e32 v130, v139, v139
	v_max_f32_e32 v131, v138, v138
	v_max_f32_e32 v130, v131, v130
	v_max3_f32 v130, v136, v137, v130
	s_nop 1
	v_mov_b32_dpp v131, v130 quad_perm:[1,0,3,2] row_mask:0xf bank_mask:0xf bound_ctrl:1
	v_max_f32_e32 v131, v131, v131
	v_max_f32_e32 v130, v130, v131
	s_nop 1
	v_mov_b32_dpp v131, v130 quad_perm:[2,3,0,1] row_mask:0xf bank_mask:0xf bound_ctrl:1
	v_max_f32_e32 v131, v131, v131
	v_max_f32_e32 v130, v130, v131
	s_nop 1
	v_mov_b32_dpp v131, v130 row_ror:4 row_mask:0xf bank_mask:0xf bound_ctrl:1
	v_max_f32_e32 v131, v131, v131
	v_max_f32_e32 v130, v130, v131
	s_nop 1
	v_mov_b32_dpp v131, v130 row_ror:8 row_mask:0xf bank_mask:0xf bound_ctrl:1
	v_max_f32_e32 v131, v131, v131
	v_max_f32_e32 v130, v130, v131
	v_mov_b32_e32 v131, v130
	s_nop 1
	v_permlane16_swap_b32_e32 v130, v131
	v_max_f32_e32 v131, v131, v131
	v_max_f32_e32 v130, v130, v130
	v_max_f32_e32 v130, v130, v131
	v_mov_b32_e32 v131, v130
	s_nop 1
	v_permlane32_swap_b32_e32 v130, v131
	v_max_f32_e32 v131, v131, v131
	v_max_f32_e32 v130, v130, v130
	v_max_f32_e32 v130, v130, v131
	v_sub_f32_e32 v131, v136, v130
	v_exp_f32_e32 v136, v131
	v_sub_f32_e32 v131, v137, v130
	v_exp_f32_e32 v137, v131
	v_sub_f32_e32 v131, v138, v130
	v_exp_f32_e32 v138, v131
	v_sub_f32_e32 v130, v139, v130
	v_exp_f32_e32 v139, v130
	v_add_f32_e32 v130, v136, v137
	v_add_f32_e32 v130, v138, v130
	v_add_f32_e32 v130, v139, v130
	ds_write_b128 v135, v[136:139]
	s_nop 0
	v_add_f32_dpp v130, v130, v130 quad_perm:[1,0,3,2] row_mask:0xf bank_mask:0xf bound_ctrl:1
	s_nop 1
	v_add_f32_dpp v130, v130, v130 quad_perm:[2,3,0,1] row_mask:0xf bank_mask:0xf bound_ctrl:1
	s_nop 1
	v_add_f32_dpp v130, v130, v130 row_ror:4 row_mask:0xf bank_mask:0xf bound_ctrl:1
	s_nop 1
	v_add_f32_dpp v130, v130, v130 row_ror:8 row_mask:0xf bank_mask:0xf bound_ctrl:1
	v_mov_b32_e32 v131, v130
	s_nop 1
	v_permlane16_swap_b32_e32 v130, v131
	v_add_f32_e32 v130, v130, v131
	v_mov_b32_e32 v131, v130
	s_nop 1
	v_permlane32_swap_b32_e32 v130, v131
	s_and_saveexec_b64 s[2:3], vcc
	s_cbranch_execz .LBB0_879
	v_add_f32_e32 v130, v130, v131
	v_div_scale_f32 v131, s[44:45], v130, v130, 1.0
	v_rcp_f32_e32 v132, v131
	v_div_scale_f32 v135, vcc, 1.0, v130, 1.0
	s_mulk_i32 s43, 0xfc04
	v_fma_f32 v136, -v131, v132, 1.0
	v_fmac_f32_e32 v132, v136, v132
	v_mul_f32_e32 v136, v135, v132
	v_fma_f32 v137, -v131, v136, v135
	v_fmac_f32_e32 v136, v137, v132
	v_fma_f32 v131, -v131, v136, v135
	v_div_fmas_f32 v131, v131, v132, v136
	s_add_i32 s20, s20, s43
	v_div_fixup_f32 v130, v131, v130, 1.0
	v_mov_b32_e32 v131, s20
	ds_write_b32 v131, v130 offset:2048

.LBB0_1031:
	s_cmp_lt_i32 s4, 5
	s_cselect_b64 s[0:1], -1, 0
	s_cmp_gt_i32 s5, 4
	s_cselect_b64 s[2:3], -1, 0
	s_and_b64 s[0:1], s[0:1], s[2:3]
	s_andn2_b64 vcc, exec, s[0:1]
	s_cbranch_vccnz .LBB0_1155
	v_mov_b32_e32 v1, v0
	s_cmpk_gt_i32 s92, 0x7f
	v_readfirstlane_b32 s0, v1
	s_cbranch_scc1 .LBB0_1034
	s_and_b32 s4, s92, 0xffffffe0
	s_ashr_i32 s0, s0, 6
	s_and_b32 s1, s92, 31
	s_ashr_i32 s2, s4, 31
	s_add_u32 s3, s4, 0x4000
	s_waitcnt vmcnt(0)
	v_and_b32_e32 v54, 31, v1
	s_addc_u32 s2, s2, 0
	v_or_b32_e32 v2, s3, v54
	v_mov_b32_e32 v3, s2
	s_lshl_b32 s2, s0, 8
	v_lshlrev_b64 v[2:3], 12, v[2:3]
	s_ashr_i32 s3, s2, 31
	s_lshl_b32 s5, s1, 17
	v_bfe_u32 v55, v1, 5, 1
	v_lshl_or_b32 v4, v54, 12, s5
	v_mov_b32_e32 v5, 0
	s_lshl_b64 s[2:3], s[2:3], 1
	v_lshl_add_u64 v[2:3], s[96:97], 0, v[2:3]
	v_lshl_add_u64 v[6:7], s[96:97], 0, v[4:5]
	v_lshl_add_u64 v[2:3], v[2:3], 0, s[2:3]
	v_lshlrev_b32_e32 v4, 4, v55
	v_lshl_add_u64 v[6:7], v[6:7], 0, s[2:3]
	v_lshl_add_u64 v[10:11], v[2:3], 0, v[4:5]
	s_mov_b32 s2, 0x1b000000
	v_add_co_u32_e32 v2, vcc, s2, v10
	v_lshl_add_u64 v[12:13], v[6:7], 0, v[4:5]
	s_nop 0
	v_addc_co_u32_e32 v3, vcc, 0, v11, vcc
	global_load_dwordx4 v[56:59], v[2:3], off
	s_mov_b32 s2, 0x1400000
	v_add_co_u32_e32 v6, vcc, s2, v12
	s_mov_b64 s[2:3], 0x1b000000
	s_nop 0
	v_addc_co_u32_e32 v7, vcc, 0, v13, vcc
	global_load_dwordx4 v[60:63], v[6:7], off
	v_lshl_add_u64 v[50:51], v[10:11], 0, s[2:3]
	global_load_dwordx4 v[64:67], v[50:51], off offset:32
	s_mov_b64 s[2:3], 0x1400000
	v_lshl_add_u64 v[52:53], v[12:13], 0, s[2:3]
	global_load_dwordx4 v[68:71], v[52:53], off offset:32
	global_load_dwordx4 v[72:75], v[50:51], off offset:64
	global_load_dwordx4 v[76:79], v[52:53], off offset:64
	global_load_dwordx4 v[80:83], v[50:51], off offset:96
	global_load_dwordx4 v[84:87], v[52:53], off offset:96
	global_load_dwordx4 v[88:91], v[50:51], off offset:128
	global_load_dwordx4 v[92:95], v[50:51], off offset:480
	global_load_dwordx4 v[96:99], v[52:53], off offset:128
	global_load_dwordx4 v[100:103], v[50:51], off offset:160
	global_load_dwordx4 v[104:107], v[52:53], off offset:160
	global_load_dwordx4 v[108:111], v[50:51], off offset:192
	global_load_dwordx4 v[112:115], v[52:53], off offset:192
	global_load_dwordx4 v[116:119], v[50:51], off offset:224
	global_load_dwordx4 v[120:123], v[52:53], off offset:224
	global_load_dwordx4 v[124:127], v[50:51], off offset:256
	global_load_dwordx4 v[128:131], v[52:53], off offset:256
	global_load_dwordx4 v[132:135], v[50:51], off offset:288
	global_load_dwordx4 v[136:139], v[52:53], off offset:288
	global_load_dwordx4 v[140:143], v[50:51], off offset:320
	global_load_dwordx4 v[144:147], v[52:53], off offset:320
	global_load_dwordx4 v[148:151], v[50:51], off offset:352
	global_load_dwordx4 v[152:155], v[52:53], off offset:352
	global_load_dwordx4 v[156:159], v[50:51], off offset:384
	global_load_dwordx4 v[160:163], v[52:53], off offset:384
	global_load_dwordx4 v[164:167], v[50:51], off offset:416
	global_load_dwordx4 v[168:171], v[52:53], off offset:416
	global_load_dwordx4 v[172:175], v[50:51], off offset:448
	global_load_dwordx4 v[176:179], v[52:53], off offset:448
	global_load_dwordx4 v[180:183], v[52:53], off offset:480
	v_and_b32_e32 v1, 63, v1
	v_lshlrev_b32_e32 v1, 2, v1
	s_waitcnt vmcnt(30)
	v_mfma_f32_32x32x16_bf16 v[2:17], v[56:59], v[60:63], 0
	s_waitcnt vmcnt(28)
	v_mfma_f32_32x32x16_bf16 v[2:17], v[64:67], v[68:71], v[2:17]
	s_waitcnt vmcnt(26)
	v_mfma_f32_32x32x16_bf16 v[2:17], v[72:75], v[76:79], v[2:17]
	s_waitcnt vmcnt(24)
	v_mfma_f32_32x32x16_bf16 v[2:17], v[80:83], v[84:87], v[2:17]
	s_waitcnt vmcnt(21)
	v_mfma_f32_32x32x16_bf16 v[2:17], v[88:91], v[96:99], v[2:17]
	s_waitcnt vmcnt(19)
	v_mfma_f32_32x32x16_bf16 v[2:17], v[100:103], v[104:107], v[2:17]
	s_waitcnt vmcnt(17)
	v_mfma_f32_32x32x16_bf16 v[2:17], v[108:111], v[112:115], v[2:17]
	s_waitcnt vmcnt(15)
	v_mfma_f32_32x32x16_bf16 v[2:17], v[116:119], v[120:123], v[2:17]
	s_waitcnt vmcnt(13)
	v_mfma_f32_32x32x16_bf16 v[2:17], v[124:127], v[128:131], v[2:17]
	s_waitcnt vmcnt(11)
	v_mfma_f32_32x32x16_bf16 v[2:17], v[132:135], v[136:139], v[2:17]
	s_waitcnt vmcnt(9)
	v_mfma_f32_32x32x16_bf16 v[2:17], v[140:143], v[144:147], v[2:17]
	s_waitcnt vmcnt(7)
	v_mfma_f32_32x32x16_bf16 v[2:17], v[148:151], v[152:155], v[2:17]
	v_lshlrev_b32_e32 v39, 2, v54
	v_lshl_or_b32 v39, s1, 7, v39
	s_lshl_b32 s1, s0, 12
	s_add_i32 s1, s1, 0
	s_add_u32 s2, s96, 0x23b00000
	v_lshl_or_b32 v38, v55, 2, s4
	s_waitcnt vmcnt(5)
	v_mfma_f32_32x32x16_bf16 v[2:17], v[156:159], v[160:163], v[2:17]
	s_addc_u32 s3, s97, 0
	s_lshl_b32 s4, s0, 2
	s_and_b32 s4, s4, -8
	s_waitcnt vmcnt(3)
	v_mfma_f32_32x32x16_bf16 v[2:17], v[164:167], v[168:171], v[2:17]
	v_add_u32_e32 v30, s1, v1
	s_lshl_b32 s1, s0, 1
	v_add_u32_e32 v1, 0, v1
	s_waitcnt vmcnt(1)
	v_mfma_f32_32x32x16_bf16 v[2:17], v[172:175], v[176:179], v[2:17]
	v_add_u32_e32 v22, s4, v38
	v_and_or_b32 v18, s1, 2, v22
	v_ashrrev_i32_e32 v19, 31, v18
	v_lshlrev_b64 v[18:19], 12, v[18:19]
	v_or_b32_e32 v18, v18, v39
	v_lshl_add_u64 v[20:21], s[70:71], 0, v[18:19]
	s_waitcnt vmcnt(0)
	v_mfma_f32_32x32x16_bf16 v[2:17], v[92:95], v[180:183], v[2:17]
	s_nop 11
	ds_write2st64_b32 v30, v2, v3 offset1:1
	ds_write2st64_b32 v30, v4, v5 offset0:2 offset1:3
	ds_write2st64_b32 v30, v6, v7 offset0:4 offset1:5
	ds_write2st64_b32 v30, v8, v9 offset0:6 offset1:7
	ds_write2st64_b32 v30, v10, v11 offset0:8 offset1:9
	ds_write2st64_b32 v30, v12, v13 offset0:10 offset1:11
	ds_write2st64_b32 v30, v14, v15 offset0:12 offset1:13
	ds_write2st64_b32 v30, v16, v17 offset0:14 offset1:15
	s_waitcnt lgkmcnt(0)
	s_barrier
	global_load_dword v16, v[20:21], off
	v_lshl_add_u32 v14, s0, 9, v1
	ds_read2st64_b32 v[6:7], v14 offset1:16
	ds_read2st64_b32 v[10:11], v14 offset0:32 offset1:48
	ds_read2st64_b32 v[12:13], v14 offset0:64 offset1:80
	ds_read2st64_b32 v[14:15], v14 offset0:96 offset1:112
	s_or_b32 s0, s1, 1
	v_and_or_b32 v2, s0, 3, v22
	v_ashrrev_i32_e32 v3, 31, v2
	s_waitcnt lgkmcnt(3)
	v_add_f32_e32 v6, 0, v6
	v_add_f32_e32 v6, v6, v7
	s_waitcnt lgkmcnt(2)
	v_add_f32_e32 v6, v6, v10
	v_add_f32_e32 v6, v6, v11
	s_waitcnt lgkmcnt(1)
	v_add_f32_e32 v6, v6, v12
	v_add_f32_e32 v6, v6, v13
	s_waitcnt lgkmcnt(0)
	v_add_f32_e32 v6, v6, v14
	v_lshlrev_b64 v[2:3], 12, v[2:3]
	v_add_f32_e32 v6, v6, v15
	v_or_b32_e32 v2, v2, v39
	v_lshl_add_u64 v[4:5], s[2:3], 0, v[18:19]
	v_lshl_add_u64 v[8:9], s[70:71], 0, v[2:3]
	v_lshl_add_u32 v1, s0, 8, v1
	v_lshl_add_u64 v[2:3], s[2:3], 0, v[2:3]
	s_waitcnt vmcnt(0)
	v_fmac_f32_e32 v6, 0x3f9837f0, v16
	global_store_dword v[4:5], v6, off
	global_load_dword v12, v[8:9], off
	ds_read2st64_b32 v[4:5], v1 offset1:16
	ds_read2st64_b32 v[6:7], v1 offset0:32 offset1:48
	ds_read2st64_b32 v[8:9], v1 offset0:64 offset1:80
	ds_read2st64_b32 v[10:11], v1 offset0:96 offset1:112
	s_waitcnt lgkmcnt(3)
	v_add_f32_e32 v1, 0, v4
	v_add_f32_e32 v1, v1, v5
	s_waitcnt lgkmcnt(2)
	v_add_f32_e32 v1, v1, v6
	v_add_f32_e32 v1, v1, v7
	s_waitcnt lgkmcnt(1)
	v_add_f32_e32 v1, v1, v8
	v_add_f32_e32 v1, v1, v9
	s_waitcnt lgkmcnt(0)
	v_add_f32_e32 v1, v1, v10
	v_add_f32_e32 v1, v1, v11
	s_waitcnt vmcnt(0)
	v_fmac_f32_e32 v1, 0x3f9837f0, v12
	global_store_dword v[2:3], v1, off
